# lever 7: butterfly reductions in the per-token elementwise phases (O1, E1, E3) via exact DPP moves (quad_perm / row_shl+row_shr:4 bank-masked / row_ror:8) and v_permlane16_swap instead of ds_bpermute
# baseline (speedup 1.0000x reference)
; template <int D> __device__ __forceinline__ void hv_load(HVRaw& r, const bf16_t* __restrict__ src, const float* __restrict__ gain, const f32x2* __restrict__ cs, const int sub) {
;     if (D == 64) {
;         r.a = *(const u32x2*)(src + sub * 4); r.b = *(const u32x2*)(src + 32 + sub * 4);
;         r.g0 = *(const f32x4*)(gain + sub * 4); r.g1 = *(const f32x4*)(gain + 32 + sub * 4);
;         r.c0 = *(const f32x4*)(cs + sub * 4); r.c1 = *(const f32x4*)(cs + sub * 4 + 2);
;     } else {
;         r.a.x = *(const unsigned*)(src + sub * 2); r.b.x = *(const unsigned*)(src + 16 + sub * 2); r.a.y = 0u; r.b.y = 0u;
;         const f32x2 g0 = *(const f32x2*)(gain + sub * 2), g1 = *(const f32x2*)(gain + 16 + sub * 2);
;         r.g0 = (f32x4){g0.x, g0.y, 0.f, 0.f}; r.g1 = (f32x4){g1.x, g1.y, 0.f, 0.f};
;         r.c0 = *(const f32x4*)(cs + sub * 2); r.c1 = r.c0;
;     }
; }
; template <int D> __device__ __forceinline__ void hv_finish(const HVRaw& r, bool norm, bool rope, float scale, bf16_t* __restrict__ dst, const int sub) {
;     constexpr int NH = D / 16;
;     float lo[4], hi[4], cc[4], sn[4];
;     lo[0] = bf2f(r.a.x & 0xffffu); lo[1] = bf2f(r.a.x >> 16); lo[2] = bf2f(r.a.y & 0xffffu); lo[3] = bf2f(r.a.y >> 16);
;     hi[0] = bf2f(r.b.x & 0xffffu); hi[1] = bf2f(r.b.x >> 16); hi[2] = bf2f(r.b.y & 0xffffu); hi[3] = bf2f(r.b.y >> 16);
;     float ss = 0.f;
; #pragma unroll
;     for (int i = 0; i < NH; ++i) ss += lo[i] * lo[i] + hi[i] * hi[i];
; __global__ void __launch_bounds__(512, 2) mega_fwd(KArgs a) {
;     ...
;                 for (int u2 = 0; u2 < 2; ++u2) {
;                     const int ev = (e0 + u2 * NGW * 64) >> 3, t = ev / 26, hh = ev - t * 26;
;                     const int off = (hh < 16) ? hh * 64 : (hh == 16) ? 1024 : (hh < 25) ? 1152 + (hh - 17) * 64 : 1664;
;                     dsts[u2] = (hh < 16) ? QSP + ((size_t)t * 16 + hh) * 64 : (hh == 16) ? KSP + (size_t)t * 64 : (hh < 25) ? QI + ((size_t)t * 8 + (hh - 17)) * 64 : KI + (size_t)t * 64;
;                     hhs[u2] = hh;
;                     hv_load<64>(hr[u2], RA + (size_t)t * ODD_INP + off, (hh == 16) ? kg : qg, CS64 + (size_t)t * 32, lane & 7);
;                 }
; #pragma unroll
;                 for (int u2 = 0; u2 < 2; ++u2) hv_finish<64>(hr[u2], hhs[u2] <= 16, true, (hhs[u2] < 16) ? 0.125f * LOG2E : 1.0f, dsts[u2], lane & 7);
.LBB0_3408:
	s_or_b64 exec, exec, s[0:1]
	v_lshlrev_b64 v[34:35], 7, v[34:35]
	v_lshl_add_u64 v[52:53], v[32:33], 0, v[34:35]
	v_mov_b64_e32 v[34:35], s[14:15]
	v_mad_i64_i32 v[34:35], s[0:1], v44, s74, v[34:35]
	v_ashrrev_i32_e32 v47, 31, v46
	v_lshl_add_u64 v[34:35], v[46:47], 1, v[34:35]
	v_mov_b32_e32 v29, v0
	v_lshl_add_u64 v[34:35], v[34:35], 0, v[28:29]
	v_lshlrev_b64 v[32:33], 7, v[50:51]
	global_load_dwordx2 v[50:51], v[34:35], off
	global_load_dwordx2 v[54:55], v[34:35], off offset:64
	s_waitcnt vmcnt(6)
	v_lshlrev_b32_e32 v60, 16, v42
	v_and_b32_e32 v62, 0xffff0000, v42
	v_lshlrev_b32_e32 v56, 16, v43
	v_and_b32_e32 v58, 0xffff0000, v43
	v_lshlrev_b32_e32 v61, 16, v40
	v_and_b32_e32 v63, 0xffff0000, v40
	v_mov_b32_e32 v42, v60
	v_mov_b32_e32 v43, v62
	v_lshlrev_b32_e32 v57, 16, v41
	v_and_b32_e32 v59, 0xffff0000, v41
	v_mov_b32_e32 v46, v58
	v_mov_b32_e32 v47, v56
	v_mov_b32_e32 v40, v61
	v_mov_b32_e32 v41, v63
	v_pk_mul_f32 v[42:43], v[42:43], v[42:43]
	v_mov_b32_e32 v34, v59
	v_mov_b32_e32 v35, v57
	v_pk_mul_f32 v[46:47], v[46:47], v[46:47]
	v_pk_fma_f32 v[40:41], v[40:41], v[40:41], v[42:43]
	v_pk_fma_f32 v[34:35], v[34:35], v[34:35], v[46:47]
	v_add_f32_e32 v31, v40, v41
	v_add_f32_e32 v31, v35, v31
	v_add_f32_e32 v31, v34, v31
	v_mov_b32_e32 v23, s9
	v_mov_b32_e32 v27, s11
	v_cmp_eq_u32_e64 s[0:1], 16, v30
	s_nop 1
	v_mov_b32_dpp v40, v31 quad_perm:[1,0,3,2] row_mask:0xf bank_mask:0xf
	v_mov_b32_e32 v39, v0
	v_cndmask_b32_e64 v37, v23, v27, s[0:1]
	v_mov_b32_e32 v23, s8
	v_mov_b32_e32 v27, s10
	v_cndmask_b32_e64 v36, v23, v27, s[0:1]
	v_lshl_add_u64 v[34:35], s[12:13], 2, v[36:37]
	v_lshl_add_u64 v[38:39], v[34:35], 0, v[38:39]
	s_waitcnt lgkmcnt(0)
	v_add_f32_e32 v23, v31, v40
	global_load_dwordx4 v[34:37], v[38:39], off
	s_nop 0
	global_load_dwordx4 v[38:41], v[38:39], off offset:128
	v_lshlrev_b64 v[42:43], 8, v[44:45]
	v_lshl_add_u64 v[46:47], v[24:25], 0, v[42:43]
	v_lshl_add_u64 v[32:33], v[48:49], 0, v[32:33]
	global_load_dwordx4 v[42:45], v[46:47], off offset:16
	s_nop 0
	global_load_dwordx4 v[46:49], v[46:47], off
	s_nop 1
	v_mov_b32_dpp v27, v23 quad_perm:[2,3,0,1] row_mask:0xf bank_mask:0xf
	s_waitcnt vmcnt(9)
	v_mov_b32_e32 v65, v12
	s_waitcnt vmcnt(8)
	v_mov_b32_e32 v64, v16
	v_mov_b32_e32 v66, v14
	v_mov_b32_e32 v67, v10
	s_waitcnt lgkmcnt(0)
	v_add_f32_e32 v23, v23, v27
	s_nop 1
	v_mov_b32_dpp v27, v23 row_shl:4 row_mask:0xf bank_mask:0x5
	v_mov_b32_dpp v27, v23 row_shr:4 row_mask:0xf bank_mask:0xa
	v_cndmask_b32_e32 v31, 1.0, v237, vcc
	v_cmp_gt_i32_e32 vcc, 17, v26
	v_mov_b32_e32 v10, v15
	s_mov_b32 s0, 0x2fffff
	s_waitcnt lgkmcnt(0)
	v_add_f32_e32 v12, v23, v27
	v_fmamk_f32 v12, v12, 0x3c800000, v231
	v_rsq_f32_e32 v16, v12
	v_mov_b32_e32 v12, v17
	v_pk_mul_f32 v[66:67], v[66:67], v[16:17] op_sel_hi:[1,0]
	s_nop 0
	v_cndmask_b32_e32 v27, 1.0, v67, vcc
	v_cndmask_b32_e32 v26, 1.0, v66, vcc
	v_pk_mul_f32 v[26:27], v[26:27], v[60:61]
	v_pk_mul_f32 v[10:11], v[10:11], v[16:17] op_sel_hi:[1,0]
	v_pk_mul_f32 v[14:15], v[64:65], v[16:17] op_sel_hi:[1,0]
	v_cndmask_b32_e32 v11, 1.0, v11, vcc
	v_cndmask_b32_e32 v10, 1.0, v10, vcc
	v_pk_mul_f32 v[12:13], v[12:13], v[16:17] op_sel_hi:[1,0]
	s_waitcnt vmcnt(6)
	v_pk_mul_f32 v[16:17], v[6:7], v[26:27] op_sel:[0,1] op_sel_hi:[1,0]
	v_pk_mul_f32 v[6:7], v[6:7], v[26:27]
	v_pk_mul_f32 v[10:11], v[10:11], v[62:63]
	v_cndmask_b32_e32 v15, 1.0, v15, vcc
	v_cndmask_b32_e32 v14, 1.0, v14, vcc
	v_add_f32_e32 v6, v6, v7
	v_pk_mul_f32 v[14:15], v[14:15], v[56:57]
	v_mul_f32_e32 v56, v31, v6
	v_pk_mul_f32 v[6:7], v[8:9], v[10:11] op_sel:[0,1] op_sel_hi:[1,0]
	v_cndmask_b32_e32 v13, 1.0, v13, vcc
	v_sub_f32_e32 v6, v6, v7
	v_mul_f32_e32 v57, v31, v6
	v_pk_mul_f32 v[6:7], v[8:9], v[10:11]
	v_cndmask_b32_e32 v12, 1.0, v12, vcc
	v_add_f32_e32 v6, v6, v7
	v_pk_mul_f32 v[12:13], v[12:13], v[58:59]
	v_mul_f32_e32 v58, v31, v6
	v_pk_mul_f32 v[6:7], v[2:3], v[14:15] op_sel:[0,1] op_sel_hi:[1,0]
	v_pk_mul_f32 v[2:3], v[2:3], v[14:15]
	v_sub_f32_e32 v6, v6, v7
	v_add_f32_e32 v2, v2, v3
	v_mul_f32_e32 v60, v31, v2
	v_pk_mul_f32 v[2:3], v[4:5], v[12:13] op_sel:[0,1] op_sel_hi:[1,0]
	v_mul_f32_e32 v59, v31, v6
	v_sub_f32_e32 v2, v2, v3
	v_mul_f32_e32 v61, v31, v2
	s_waitcnt vmcnt(4)
; __device__ __forceinline__ unsigned cvt_pk_bf16(float lo, float hi) { unsigned r; asm volatile("v_cvt_pk_bf16_f32 %0, %1, %2" : "=v"(r) : "v"(lo), "v"(hi)); return r; }
; __device__ __forceinline__ float bf2f(unsigned h) { return __uint_as_float(h << 16); }
; template <int D> __device__ __forceinline__ void hv_finish(const HVRaw& r, bool norm, bool rope, float scale, bf16_t* __restrict__ dst, const int sub) {
;     constexpr int NH = D / 16;
;     float lo[4], hi[4], cc[4], sn[4];
;     lo[0] = bf2f(r.a.x & 0xffffu); lo[1] = bf2f(r.a.x >> 16); lo[2] = bf2f(r.a.y & 0xffffu); lo[3] = bf2f(r.a.y >> 16);
;     hi[0] = bf2f(r.b.x & 0xffffu); hi[1] = bf2f(r.b.x >> 16); hi[2] = bf2f(r.b.y & 0xffffu); hi[3] = bf2f(r.b.y >> 16);
;     float ss = 0.f;
; #pragma unroll
;     for (int i = 0; i < NH; ++i) ss += lo[i] * lo[i] + hi[i] * hi[i];
;     ss += __shfl_xor(ss, 1); ss += __shfl_xor(ss, 2); ss += __shfl_xor(ss, 4);
;     const float rs = norm ? __builtin_amdgcn_rsqf(ss * (1.0f / D) + EPS) : 1.0f;
; #pragma unroll
;     for (int i = 0; i < NH; ++i) { lo[i] *= norm ? rs * r.g0[i] : 1.0f; hi[i] *= norm ? rs * r.g1[i] : 1.0f; }
;     cc[0] = r.c0[0]; sn[0] = r.c0[1]; cc[1] = r.c0[2]; sn[1] = r.c0[3]; cc[2] = r.c1[0]; sn[2] = r.c1[1]; cc[3] = r.c1[2]; sn[3] = r.c1[3];
;     float ol[4], oh[4];
; #pragma unroll
;     for (int i = 0; i < NH; ++i) {
;         const float c = rope ? cc[i] : 1.0f, sv = rope ? sn[i] : 0.0f;
;         ol[i] = (lo[i] * c - hi[i] * sv) * scale; oh[i] = (hi[i] * c + lo[i] * sv) * scale;
;     }
;     if (NH == 4) {
;         u32x2 w0, w1; w0.x = pg8::cvt_pk_bf16(ol[0], ol[1]); w0.y = pg8::cvt_pk_bf16(ol[2], ol[3]); w1.x = pg8::cvt_pk_bf16(oh[0], oh[1]); w1.y = pg8::cvt_pk_bf16(oh[2], oh[3]);
;         *(u32x2*)(dst + sub * 4) = w0; *(u32x2*)(dst + 32 + sub * 4) = w1;
;     } else {
;         *(unsigned*)(dst + sub * 2) = pg8::cvt_pk_bf16(ol[0], ol[1]); *(unsigned*)(dst + 16 + sub * 2) = pg8::cvt_pk_bf16(oh[0], oh[1]);
;     }
; }
	v_lshlrev_b32_e32 v2, 16, v55
	v_and_b32_e32 v6, 0xffff0000, v55
	v_lshlrev_b32_e32 v3, 16, v51
	v_and_b32_e32 v7, 0xffff0000, v51
	v_mov_b32_e32 v10, v6
	v_mov_b32_e32 v11, v2
	v_mov_b32_e32 v8, v7
	v_mov_b32_e32 v9, v3
	v_pk_mul_f32 v[10:11], v[10:11], v[10:11]
	v_and_b32_e32 v14, 0xffff0000, v54
	v_pk_fma_f32 v[8:9], v[8:9], v[8:9], v[10:11]
	v_lshlrev_b32_e32 v10, 16, v54
	v_sub_f32_e32 v16, v16, v17
	v_lshlrev_b32_e32 v11, 16, v50
	v_and_b32_e32 v15, 0xffff0000, v50
	v_mov_b32_e32 v26, v10
	v_mov_b32_e32 v27, v14
	v_mul_f32_e32 v23, v31, v16
	v_mov_b32_e32 v16, v11
	v_mov_b32_e32 v17, v15
	v_pk_mul_f32 v[26:27], v[26:27], v[26:27]
	v_pk_mul_f32 v[4:5], v[4:5], v[12:13]
	v_pk_fma_f32 v[16:17], v[16:17], v[16:17], v[26:27]
	v_add_f32_e32 v4, v4, v5
	v_add_f32_e32 v16, v16, v17
	v_add_f32_e32 v9, v9, v16
	v_add_f32_e32 v8, v8, v9
	s_nop 1
	v_mov_b32_dpp v9, v8 quad_perm:[1,0,3,2] row_mask:0xf bank_mask:0xf
	v_mul_f32_e32 v12, v31, v4
	v_cvt_pk_bf16_f32 v4, v23, v57
	v_cvt_pk_bf16_f32 v5, v59, v61
	v_cmp_gt_i32_e32 vcc, 17, v30
	s_waitcnt lgkmcnt(0)
	v_add_f32_e32 v16, v8, v9
	s_nop 1
	v_mov_b32_dpp v17, v16 quad_perm:[2,3,0,1] row_mask:0xf bank_mask:0xf
	v_cvt_pk_bf16_f32 v8, v56, v58
	v_cvt_pk_bf16_f32 v9, v60, v12
	v_lshl_add_u64 v[12:13], v[52:53], 0, v[28:29]
	global_store_dwordx2 v[12:13], v[4:5], off
	global_store_dwordx2 v[12:13], v[8:9], off offset:64
	s_waitcnt lgkmcnt(0)
	v_add_f32_e32 v16, v16, v17
	s_nop 1
	v_mov_b32_dpp v17, v16 row_shl:4 row_mask:0xf bank_mask:0x5
	v_mov_b32_dpp v17, v16 row_shr:4 row_mask:0xf bank_mask:0xa
	s_waitcnt vmcnt(4)
	v_mov_b32_e32 v4, v40
	v_mov_b32_e32 v5, v36
	v_mov_b32_e32 v12, v38
	v_mov_b32_e32 v13, v34
	s_waitcnt lgkmcnt(0)
	v_add_f32_e32 v8, v16, v17
	v_fmamk_f32 v8, v8, 0x3c800000, v231
	v_rsq_f32_e32 v8, v8
	v_mov_b32_e32 v36, v41
	v_mov_b32_e32 v34, v39
	v_pk_mul_f32 v[4:5], v[4:5], v[8:9] op_sel_hi:[1,0]
	v_pk_mul_f32 v[12:13], v[12:13], v[8:9] op_sel_hi:[1,0]
	v_cndmask_b32_e32 v5, 1.0, v5, vcc
	v_cndmask_b32_e32 v4, 1.0, v4, vcc
	v_cndmask_b32_e32 v13, 1.0, v13, vcc
	v_cndmask_b32_e32 v12, 1.0, v12, vcc
	v_pk_mul_f32 v[2:3], v[4:5], v[2:3]
	v_pk_mul_f32 v[4:5], v[36:37], v[8:9] op_sel_hi:[1,0]
	v_pk_mul_f32 v[10:11], v[12:13], v[10:11]
	v_cndmask_b32_e32 v5, 1.0, v5, vcc
	v_cndmask_b32_e32 v4, 1.0, v4, vcc
	v_pk_mul_f32 v[4:5], v[4:5], v[6:7]
	s_waitcnt vmcnt(2)
	v_pk_mul_f32 v[6:7], v[46:47], v[10:11] op_sel:[0,1] op_sel_hi:[1,0]
	v_pk_mul_f32 v[12:13], v[34:35], v[8:9] op_sel_hi:[1,0]
	v_sub_f32_e32 v6, v6, v7
	v_cndmask_b32_e32 v13, 1.0, v13, vcc
	v_cndmask_b32_e32 v12, 1.0, v12, vcc
	v_mul_f32_e32 v8, v21, v6
	v_pk_mul_f32 v[6:7], v[46:47], v[10:11]
	v_pk_mul_f32 v[12:13], v[12:13], v[14:15]
	v_add_f32_e32 v6, v6, v7
	v_mul_f32_e32 v9, v21, v6
	v_pk_mul_f32 v[6:7], v[48:49], v[12:13] op_sel:[0,1] op_sel_hi:[1,0]
	v_cmp_lt_i32_e32 vcc, s0, v19
	v_sub_f32_e32 v6, v6, v7
	v_mul_f32_e32 v10, v21, v6
	v_pk_mul_f32 v[6:7], v[48:49], v[12:13]
	s_or_b64 s[16:17], vcc, s[16:17]
	v_add_f32_e32 v6, v6, v7
	v_mul_f32_e32 v11, v21, v6
	v_pk_mul_f32 v[6:7], v[42:43], v[2:3] op_sel:[0,1] op_sel_hi:[1,0]
	v_pk_mul_f32 v[2:3], v[42:43], v[2:3]
	v_sub_f32_e32 v6, v6, v7
	v_add_f32_e32 v2, v2, v3
	v_mul_f32_e32 v7, v21, v2
	v_pk_mul_f32 v[2:3], v[44:45], v[4:5] op_sel:[0,1] op_sel_hi:[1,0]
	v_mul_f32_e32 v6, v21, v6
	v_sub_f32_e32 v2, v2, v3
	v_mul_f32_e32 v12, v21, v2
	v_pk_mul_f32 v[2:3], v[44:45], v[4:5]
	v_add_u32_e32 v19, 0x40000, v19
	v_add_f32_e32 v2, v2, v3
	v_mul_f32_e32 v5, v21, v2
	v_cvt_pk_bf16_f32 v2, v8, v10
	v_cvt_pk_bf16_f32 v3, v6, v12
	v_cvt_pk_bf16_f32 v4, v9, v11
	v_cvt_pk_bf16_f32 v5, v7, v5
	v_lshl_add_u64 v[6:7], v[32:33], 0, v[28:29]
	global_store_dwordx2 v[6:7], v[2:3], off
	global_store_dwordx2 v[6:7], v[4:5], off offset:64
	s_andn2_b64 exec, exec, s[16:17]
	s_cbranch_execz .LBB0_3445

; __device__ __forceinline__ unsigned cvt_pk_bf16(float lo, float hi) { unsigned r; asm volatile("v_cvt_pk_bf16_f32 %0, %1, %2" : "=v"(r) : "v"(lo), "v"(hi)); return r; }
; __device__ __forceinline__ float bf2f(unsigned h) { return __uint_as_float(h << 16); }
; template <int D> __device__ __forceinline__ void norm_vec(const bf16_t* __restrict__ src, const float* __restrict__ gain, bf16_t* __restrict__ dst, const int sub) {
;     const u32x4 raw = *(const u32x4*)(src + sub * 8);
;     float v[8];
;     v[0] = bf2f(raw.x & 0xffffu); v[1] = bf2f(raw.x >> 16); v[2] = bf2f(raw.y & 0xffffu); v[3] = bf2f(raw.y >> 16);
;     v[4] = bf2f(raw.z & 0xffffu); v[5] = bf2f(raw.z >> 16); v[6] = bf2f(raw.w & 0xffffu); v[7] = bf2f(raw.w >> 16);
;     float ss = 0.f;
; #pragma unroll
;     for (int i = 0; i < 8; ++i) ss += v[i] * v[i];
; #pragma unroll
;     for (int o = 1; o < D / 8; o <<= 1) ss += __shfl_xor(ss, o);
;     const float rs = __builtin_amdgcn_rsqf(ss * (1.0f / D) + EPS);
;     const f32x4 g0 = *(const f32x4*)(gain + sub * 8), g1 = *(const f32x4*)(gain + sub * 8 + 4);
;     u32x4 w; w.x = pg8::cvt_pk_bf16(v[0] * rs * g0[0], v[1] * rs * g0[1]); w.y = pg8::cvt_pk_bf16(v[2] * rs * g0[2], v[3] * rs * g0[3]);
;     w.z = pg8::cvt_pk_bf16(v[4] * rs * g1[0], v[5] * rs * g1[1]); w.w = pg8::cvt_pk_bf16(v[6] * rs * g1[2], v[7] * rs * g1[3]);
;     *(u32x4*)(dst + sub * 8) = w;
; }
; __global__ void __launch_bounds__(512, 2) mega_fwd(KArgs a) {
;     ...
;             for (int e = gw * 64 + lane; e < T_ * 32; e += NGW * 64) {
;                 const int t = e >> 5;
;                 norm_vec<256>(RA + (size_t)t * EVEN_INP, qlg, CQKV + (size_t)t * 384, lane & 31);
;             }
.LBB0_4068:
	v_ashrrev_i32_e32 v17, 5, v16
	v_mad_i64_i32 v[18:19], s[14:15], v17, s96, v[10:11]
	global_load_dwordx4 v[28:31], v[18:19], off
	v_add_u32_e32 v44, 0x1000, v17
	v_mad_i64_i32 v[18:19], s[14:15], v44, s96, v[10:11]
	global_load_dwordx4 v[32:35], v[18:19], off
	v_add_u32_e32 v45, 0x2000, v17
	v_mad_i64_i32 v[18:19], s[14:15], v45, s96, v[10:11]
	global_load_dwordx4 v[36:39], v[18:19], off
	v_add_u32_e32 v46, 0x3000, v17
	v_mad_i64_i32 v[18:19], s[14:15], v46, s96, v[10:11]
	global_load_dwordx4 v[40:43], v[18:19], off
	s_waitcnt vmcnt(3)
	v_lshlrev_b32_e32 v22, 16, v28
	v_and_b32_e32 v28, 0xffff0000, v28
	v_mul_f32_e32 v26, v28, v28
	v_lshlrev_b32_e32 v23, 16, v29
	v_fmac_f32_e32 v26, v22, v22
	v_and_b32_e32 v29, 0xffff0000, v29
	v_fmac_f32_e32 v26, v23, v23
	v_lshlrev_b32_e32 v24, 16, v30
	v_fmac_f32_e32 v26, v29, v29
	v_and_b32_e32 v30, 0xffff0000, v30
	v_fmac_f32_e32 v26, v24, v24
	v_lshlrev_b32_e32 v25, 16, v31
	v_fmac_f32_e32 v26, v30, v30
	v_and_b32_e32 v31, 0xffff0000, v31
	v_fmac_f32_e32 v26, v25, v25
	v_fmac_f32_e32 v26, v31, v31
	s_nop 1
	v_mov_b32_dpp v27, v26 quad_perm:[1,0,3,2] row_mask:0xf bank_mask:0xf
	s_waitcnt lgkmcnt(0)
	v_add_f32_e32 v26, v26, v27
	s_nop 1
	v_mov_b32_dpp v27, v26 quad_perm:[2,3,0,1] row_mask:0xf bank_mask:0xf
	s_waitcnt lgkmcnt(0)
	v_add_f32_e32 v26, v26, v27
	s_nop 1
	v_mov_b32_dpp v27, v26 row_shl:4 row_mask:0xf bank_mask:0x5
	v_mov_b32_dpp v27, v26 row_shr:4 row_mask:0xf bank_mask:0xa
	s_waitcnt lgkmcnt(0)
	v_add_f32_e32 v26, v26, v27
	s_nop 1
	v_mov_b32_dpp v27, v26 row_ror:8 row_mask:0xf bank_mask:0xf
	s_waitcnt lgkmcnt(0)
	v_add_f32_e32 v26, v26, v27
	v_mov_b32_e32 v27, v26
	s_nop 1
	v_permlane16_swap_b32 v27, v26
	s_waitcnt lgkmcnt(0)
	v_add_f32_e32 v26, v26, v27
	v_fmamk_f32 v26, v26, 0x3b800000, v231
	v_rsq_f32_e32 v26, v26
	s_nop 0
	v_mul_f32_e32 v22, v26, v22
	v_mul_f32_e32 v28, v26, v28
	v_mul_f32_e32 v22, v2, v22
	v_mul_f32_e32 v28, v3, v28
	v_cvt_pk_bf16_f32 v28, v22, v28
	v_mul_f32_e32 v22, v26, v23
	v_mul_f32_e32 v29, v26, v29
	v_mul_f32_e32 v22, v4, v22
	v_mul_f32_e32 v29, v5, v29
	v_cvt_pk_bf16_f32 v29, v22, v29
	v_mul_f32_e32 v22, v26, v24
	v_mul_f32_e32 v30, v26, v30
	v_mul_f32_e32 v22, v6, v22
	v_mul_f32_e32 v30, v7, v30
	v_cvt_pk_bf16_f32 v30, v22, v30
	v_mul_f32_e32 v22, v26, v25
	v_mul_f32_e32 v31, v26, v31
	v_mul_f32_e32 v22, v8, v22
	v_mul_f32_e32 v31, v9, v31
	v_cvt_pk_bf16_f32 v31, v22, v31
	v_mad_i64_i32 v[22:23], s[14:15], v17, s73, v[12:13]
	global_store_dwordx4 v[22:23], v[28:31], off
	s_nop 1
	s_waitcnt vmcnt(3)
	v_lshlrev_b32_e32 v22, 16, v32
	v_and_b32_e32 v32, 0xffff0000, v32
	v_mul_f32_e32 v26, v32, v32
	v_lshlrev_b32_e32 v23, 16, v33
	v_fmac_f32_e32 v26, v22, v22
	v_and_b32_e32 v33, 0xffff0000, v33
	v_fmac_f32_e32 v26, v23, v23
	v_lshlrev_b32_e32 v24, 16, v34
	v_fmac_f32_e32 v26, v33, v33
	v_and_b32_e32 v34, 0xffff0000, v34
	v_fmac_f32_e32 v26, v24, v24
	v_lshlrev_b32_e32 v25, 16, v35
	v_fmac_f32_e32 v26, v34, v34
	v_and_b32_e32 v35, 0xffff0000, v35
	v_fmac_f32_e32 v26, v25, v25
	v_fmac_f32_e32 v26, v35, v35
	s_nop 1
	v_mov_b32_dpp v27, v26 quad_perm:[1,0,3,2] row_mask:0xf bank_mask:0xf
	s_waitcnt lgkmcnt(0)
	v_add_f32_e32 v26, v26, v27
	s_nop 1
	v_mov_b32_dpp v27, v26 quad_perm:[2,3,0,1] row_mask:0xf bank_mask:0xf
	s_waitcnt lgkmcnt(0)
	v_add_f32_e32 v26, v26, v27
	s_nop 1
	v_mov_b32_dpp v27, v26 row_shl:4 row_mask:0xf bank_mask:0x5
	v_mov_b32_dpp v27, v26 row_shr:4 row_mask:0xf bank_mask:0xa
	s_waitcnt lgkmcnt(0)
	v_add_f32_e32 v26, v26, v27
	s_nop 1
	v_mov_b32_dpp v27, v26 row_ror:8 row_mask:0xf bank_mask:0xf
	s_waitcnt lgkmcnt(0)
	v_add_f32_e32 v26, v26, v27
	v_mov_b32_e32 v27, v26
	s_nop 1
	v_permlane16_swap_b32 v27, v26
	s_waitcnt lgkmcnt(0)
	v_add_f32_e32 v26, v26, v27
	v_fmamk_f32 v26, v26, 0x3b800000, v231
	v_rsq_f32_e32 v26, v26
	s_nop 0
	v_mul_f32_e32 v22, v26, v22
	v_mul_f32_e32 v32, v26, v32
	v_mul_f32_e32 v22, v2, v22
	v_mul_f32_e32 v32, v3, v32
	v_cvt_pk_bf16_f32 v32, v22, v32
	v_mul_f32_e32 v22, v26, v23
	v_mul_f32_e32 v33, v26, v33
	v_mul_f32_e32 v22, v4, v22
	v_mul_f32_e32 v33, v5, v33
	v_cvt_pk_bf16_f32 v33, v22, v33
	v_mul_f32_e32 v22, v26, v24
	v_mul_f32_e32 v34, v26, v34
	v_mul_f32_e32 v22, v6, v22
	v_mul_f32_e32 v34, v7, v34
	v_cvt_pk_bf16_f32 v34, v22, v34
	v_mul_f32_e32 v22, v26, v25
	v_mul_f32_e32 v35, v26, v35
	v_mul_f32_e32 v22, v8, v22
	v_mul_f32_e32 v35, v9, v35
	v_cvt_pk_bf16_f32 v35, v22, v35
	v_mad_i64_i32 v[22:23], s[14:15], v44, s73, v[12:13]
	global_store_dwordx4 v[22:23], v[32:35], off
	s_nop 1
	s_waitcnt vmcnt(3)
; __device__ __forceinline__ unsigned cvt_pk_bf16(float lo, float hi) { unsigned r; asm volatile("v_cvt_pk_bf16_f32 %0, %1, %2" : "=v"(r) : "v"(lo), "v"(hi)); return r; }
; __device__ __forceinline__ float bf2f(unsigned h) { return __uint_as_float(h << 16); }
; template <int D> __device__ __forceinline__ void norm_vec(const bf16_t* __restrict__ src, const float* __restrict__ gain, bf16_t* __restrict__ dst, const int sub) {
;     const u32x4 raw = *(const u32x4*)(src + sub * 8);
;     float v[8];
;     v[0] = bf2f(raw.x & 0xffffu); v[1] = bf2f(raw.x >> 16); v[2] = bf2f(raw.y & 0xffffu); v[3] = bf2f(raw.y >> 16);
;     v[4] = bf2f(raw.z & 0xffffu); v[5] = bf2f(raw.z >> 16); v[6] = bf2f(raw.w & 0xffffu); v[7] = bf2f(raw.w >> 16);
;     float ss = 0.f;
; #pragma unroll
;     for (int i = 0; i < 8; ++i) ss += v[i] * v[i];
; #pragma unroll
;     for (int o = 1; o < D / 8; o <<= 1) ss += __shfl_xor(ss, o);
;     const float rs = __builtin_amdgcn_rsqf(ss * (1.0f / D) + EPS);
;     const f32x4 g0 = *(const f32x4*)(gain + sub * 8), g1 = *(const f32x4*)(gain + sub * 8 + 4);
;     u32x4 w; w.x = pg8::cvt_pk_bf16(v[0] * rs * g0[0], v[1] * rs * g0[1]); w.y = pg8::cvt_pk_bf16(v[2] * rs * g0[2], v[3] * rs * g0[3]);
;     w.z = pg8::cvt_pk_bf16(v[4] * rs * g1[0], v[5] * rs * g1[1]); w.w = pg8::cvt_pk_bf16(v[6] * rs * g1[2], v[7] * rs * g1[3]);
;     *(u32x4*)(dst + sub * 8) = w;
; }
	v_lshlrev_b32_e32 v22, 16, v36
	v_and_b32_e32 v36, 0xffff0000, v36
	v_mul_f32_e32 v26, v36, v36
	v_lshlrev_b32_e32 v23, 16, v37
	v_fmac_f32_e32 v26, v22, v22
	v_and_b32_e32 v37, 0xffff0000, v37
	v_fmac_f32_e32 v26, v23, v23
	v_lshlrev_b32_e32 v24, 16, v38
	v_fmac_f32_e32 v26, v37, v37
	v_and_b32_e32 v38, 0xffff0000, v38
	v_fmac_f32_e32 v26, v24, v24
	v_lshlrev_b32_e32 v25, 16, v39
	v_fmac_f32_e32 v26, v38, v38
	v_and_b32_e32 v39, 0xffff0000, v39
	v_fmac_f32_e32 v26, v25, v25
	v_fmac_f32_e32 v26, v39, v39
	s_nop 1
	v_mov_b32_dpp v27, v26 quad_perm:[1,0,3,2] row_mask:0xf bank_mask:0xf
	s_waitcnt lgkmcnt(0)
	v_add_f32_e32 v26, v26, v27
	s_nop 1
	v_mov_b32_dpp v27, v26 quad_perm:[2,3,0,1] row_mask:0xf bank_mask:0xf
	s_waitcnt lgkmcnt(0)
	v_add_f32_e32 v26, v26, v27
	s_nop 1
	v_mov_b32_dpp v27, v26 row_shl:4 row_mask:0xf bank_mask:0x5
	v_mov_b32_dpp v27, v26 row_shr:4 row_mask:0xf bank_mask:0xa
	s_waitcnt lgkmcnt(0)
	v_add_f32_e32 v26, v26, v27
	s_nop 1
	v_mov_b32_dpp v27, v26 row_ror:8 row_mask:0xf bank_mask:0xf
	s_waitcnt lgkmcnt(0)
	v_add_f32_e32 v26, v26, v27
	v_mov_b32_e32 v27, v26
	s_nop 1
	v_permlane16_swap_b32 v27, v26
	s_waitcnt lgkmcnt(0)
	v_add_f32_e32 v26, v26, v27
	v_fmamk_f32 v26, v26, 0x3b800000, v231
	v_rsq_f32_e32 v26, v26
	s_nop 0
	v_mul_f32_e32 v22, v26, v22
	v_mul_f32_e32 v36, v26, v36
	v_mul_f32_e32 v22, v2, v22
	v_mul_f32_e32 v36, v3, v36
	v_cvt_pk_bf16_f32 v36, v22, v36
	v_mul_f32_e32 v22, v26, v23
	v_mul_f32_e32 v37, v26, v37
	v_mul_f32_e32 v22, v4, v22
	v_mul_f32_e32 v37, v5, v37
	v_cvt_pk_bf16_f32 v37, v22, v37
	v_mul_f32_e32 v22, v26, v24
	v_mul_f32_e32 v38, v26, v38
	v_mul_f32_e32 v22, v6, v22
	v_mul_f32_e32 v38, v7, v38
	v_cvt_pk_bf16_f32 v38, v22, v38
	v_mul_f32_e32 v22, v26, v25
	v_mul_f32_e32 v39, v26, v39
	v_mul_f32_e32 v22, v8, v22
	v_mul_f32_e32 v39, v9, v39
	v_cvt_pk_bf16_f32 v39, v22, v39
	v_mad_i64_i32 v[22:23], s[14:15], v45, s73, v[12:13]
	global_store_dwordx4 v[22:23], v[36:39], off
	s_nop 1
	s_waitcnt vmcnt(3)
	v_lshlrev_b32_e32 v22, 16, v40
	v_and_b32_e32 v40, 0xffff0000, v40
	v_mul_f32_e32 v26, v40, v40
	v_lshlrev_b32_e32 v23, 16, v41
	v_fmac_f32_e32 v26, v22, v22
	v_and_b32_e32 v41, 0xffff0000, v41
	v_fmac_f32_e32 v26, v23, v23
	v_lshlrev_b32_e32 v24, 16, v42
	v_fmac_f32_e32 v26, v41, v41
	v_and_b32_e32 v42, 0xffff0000, v42
	v_fmac_f32_e32 v26, v24, v24
	v_lshlrev_b32_e32 v25, 16, v43
	v_fmac_f32_e32 v26, v42, v42
	v_and_b32_e32 v43, 0xffff0000, v43
	v_fmac_f32_e32 v26, v25, v25
	v_fmac_f32_e32 v26, v43, v43
	s_nop 1
	v_mov_b32_dpp v27, v26 quad_perm:[1,0,3,2] row_mask:0xf bank_mask:0xf
	s_waitcnt lgkmcnt(0)
	v_add_f32_e32 v26, v26, v27
	s_nop 1
	v_mov_b32_dpp v27, v26 quad_perm:[2,3,0,1] row_mask:0xf bank_mask:0xf
	s_waitcnt lgkmcnt(0)
	v_add_f32_e32 v26, v26, v27
	s_nop 1
	v_mov_b32_dpp v27, v26 row_shl:4 row_mask:0xf bank_mask:0x5
	v_mov_b32_dpp v27, v26 row_shr:4 row_mask:0xf bank_mask:0xa
	s_waitcnt lgkmcnt(0)
	v_add_f32_e32 v26, v26, v27
	s_nop 1
	v_mov_b32_dpp v27, v26 row_ror:8 row_mask:0xf bank_mask:0xf
	s_waitcnt lgkmcnt(0)
	v_add_f32_e32 v26, v26, v27
	v_mov_b32_e32 v27, v26
	s_nop 1
	v_permlane16_swap_b32 v27, v26
	s_waitcnt lgkmcnt(0)
	v_add_f32_e32 v26, v26, v27
	v_fmamk_f32 v26, v26, 0x3b800000, v231
	v_rsq_f32_e32 v26, v26
	s_nop 0
	v_mul_f32_e32 v22, v26, v22
	v_mul_f32_e32 v40, v26, v40
	v_mul_f32_e32 v22, v2, v22
	v_mul_f32_e32 v40, v3, v40
	v_cvt_pk_bf16_f32 v40, v22, v40
	v_mul_f32_e32 v22, v26, v23
	v_mul_f32_e32 v41, v26, v41
	v_mul_f32_e32 v22, v4, v22
	v_mul_f32_e32 v41, v5, v41
	v_cvt_pk_bf16_f32 v41, v22, v41
	v_mul_f32_e32 v22, v26, v24
	v_mul_f32_e32 v42, v26, v42
	v_mul_f32_e32 v22, v6, v22
	v_mul_f32_e32 v42, v7, v42
	v_cvt_pk_bf16_f32 v42, v22, v42
	v_mul_f32_e32 v22, v26, v25
	v_mul_f32_e32 v43, v26, v43
	v_mul_f32_e32 v22, v8, v22
	v_mul_f32_e32 v43, v9, v43
	v_cvt_pk_bf16_f32 v43, v22, v43
	v_mad_i64_i32 v[22:23], s[14:15], v46, s73, v[12:13]
	global_store_dwordx4 v[22:23], v[40:43], off
	s_nop 1

; __device__ __forceinline__ unsigned cvt_pk_bf16(float lo, float hi) { unsigned r; asm volatile("v_cvt_pk_bf16_f32 %0, %1, %2" : "=v"(r) : "v"(lo), "v"(hi)); return r; }
; __device__ __forceinline__ float bf2f(unsigned h) { return __uint_as_float(h << 16); }
; template <int D> __device__ __forceinline__ void norm_vec(const bf16_t* __restrict__ src, const float* __restrict__ gain, bf16_t* __restrict__ dst, const int sub) {
;     const u32x4 raw = *(const u32x4*)(src + sub * 8);
;     float v[8];
;     v[0] = bf2f(raw.x & 0xffffu); v[1] = bf2f(raw.x >> 16); v[2] = bf2f(raw.y & 0xffffu); v[3] = bf2f(raw.y >> 16);
;     v[4] = bf2f(raw.z & 0xffffu); v[5] = bf2f(raw.z >> 16); v[6] = bf2f(raw.w & 0xffffu); v[7] = bf2f(raw.w >> 16);
;     float ss = 0.f;
; #pragma unroll
;     for (int i = 0; i < 8; ++i) ss += v[i] * v[i];
; #pragma unroll
;     for (int o = 1; o < D / 8; o <<= 1) ss += __shfl_xor(ss, o);
;     const float rs = __builtin_amdgcn_rsqf(ss * (1.0f / D) + EPS);
;     const f32x4 g0 = *(const f32x4*)(gain + sub * 8), g1 = *(const f32x4*)(gain + sub * 8 + 4);
;     u32x4 w; w.x = pg8::cvt_pk_bf16(v[0] * rs * g0[0], v[1] * rs * g0[1]); w.y = pg8::cvt_pk_bf16(v[2] * rs * g0[2], v[3] * rs * g0[3]);
;     w.z = pg8::cvt_pk_bf16(v[4] * rs * g1[0], v[5] * rs * g1[1]); w.w = pg8::cvt_pk_bf16(v[6] * rs * g1[2], v[7] * rs * g1[3]);
;     *(u32x4*)(dst + sub * 8) = w;
; }
; __global__ void __launch_bounds__(512, 2) mega_fwd(KArgs a) {
;     ...
;             for (int e = gw * 64 + lane; e < T_ * 16; e += NGW * 64) {
;                 const int t = e >> 4;
;                 norm_vec<128>(RA + (size_t)t * EVEN_INP + 256, kvlg, CQKV + (size_t)t * 384 + 256, lane & 15);
;             }
.LBB0_4071:
	s_load_dwordx2 s[12:13], s[0:1], 0x100
	v_ashrrev_i32_e32 v11, 4, v12
	s_waitcnt lgkmcnt(0)
	v_mov_b64_e32 v[16:17], s[12:13]
	v_mad_i64_i32 v[16:17], s[12:13], v11, s96, v[16:17]
	s_movk_i32 s12, 0xed00
	s_nop 0
	v_mad_i64_i32 v[20:21], s[12:13], v11, s12, v[16:17]
	v_mov_b32_e32 v11, v0
	v_lshl_add_u64 v[16:17], v[16:17], 0, v[10:11]
	v_add_co_u32_e32 v16, vcc, 0x8c00000, v16
	v_lshl_add_u64 v[20:21], v[20:21], 0, v[10:11]
	s_nop 0
	v_addc_co_u32_e32 v17, vcc, 0, v17, vcc
	global_load_dwordx4 v[16:19], v[16:17], off offset:512
	v_add_co_u32_e32 v20, vcc, 0x16c00000, v20
	v_add_u32_e32 v11, 0x20000, v12
	s_nop 0
	v_addc_co_u32_e32 v21, vcc, 0, v21, vcc
	v_cmp_lt_i32_e32 vcc, s75, v12
	s_or_b64 s[2:3], vcc, s[2:3]
	v_mov_b32_e32 v12, v11
	s_waitcnt vmcnt(0)
	v_and_b32_e32 v15, 0xffff0000, v16
	v_lshlrev_b32_e32 v13, 16, v16
	v_mul_f32_e32 v27, v15, v15
	v_lshlrev_b32_e32 v24, 16, v17
	v_fmac_f32_e32 v27, v13, v13
	v_and_b32_e32 v25, 0xffff0000, v17
	v_fmac_f32_e32 v27, v24, v24
	v_lshlrev_b32_e32 v26, 16, v18
	v_fmac_f32_e32 v27, v25, v25
	v_and_b32_e32 v18, 0xffff0000, v18
	v_fmac_f32_e32 v27, v26, v26
	v_and_b32_e32 v22, 0xffff0000, v19
	v_lshlrev_b32_e32 v23, 16, v19
	v_fmac_f32_e32 v27, v18, v18
	v_pk_mul_f32 v[16:17], v[22:23], v[22:23]
	s_nop 0
	v_add_f32_e32 v17, v17, v27
	v_add_f32_e32 v16, v16, v17
	s_nop 1
	v_mov_b32_dpp v17, v16 quad_perm:[1,0,3,2] row_mask:0xf bank_mask:0xf
	s_waitcnt lgkmcnt(0)
	v_add_f32_e32 v16, v16, v17
	s_nop 1
	v_mov_b32_dpp v17, v16 quad_perm:[2,3,0,1] row_mask:0xf bank_mask:0xf
	s_waitcnt lgkmcnt(0)
	v_add_f32_e32 v16, v16, v17
	s_nop 1
	v_mov_b32_dpp v17, v16 row_shl:4 row_mask:0xf bank_mask:0x5
	v_mov_b32_dpp v17, v16 row_shr:4 row_mask:0xf bank_mask:0xa
	s_waitcnt lgkmcnt(0)
	v_add_f32_e32 v16, v16, v17
	s_nop 1
	v_mov_b32_dpp v17, v16 row_ror:8 row_mask:0xf bank_mask:0xf
	s_waitcnt lgkmcnt(0)
	v_add_f32_e32 v16, v16, v17
	v_fmamk_f32 v16, v16, 0x3c000000, v231
	v_rsq_f32_e32 v19, v16
	s_nop 0
	v_mul_f32_e32 v13, v19, v13
	v_mul_f32_e32 v15, v19, v15
	v_mul_f32_e32 v13, v2, v13
	v_mul_f32_e32 v15, v3, v15
	v_cvt_pk_bf16_f32 v16, v13, v15
	v_mul_f32_e32 v13, v19, v24
	v_mul_f32_e32 v15, v19, v25
	v_mul_f32_e32 v13, v4, v13
	v_mul_f32_e32 v15, v5, v15
	v_cvt_pk_bf16_f32 v17, v13, v15
	v_mul_f32_e32 v13, v19, v26
	v_mul_f32_e32 v15, v19, v18
	v_mul_f32_e32 v13, v6, v13
	v_mul_f32_e32 v15, v7, v15
	v_cvt_pk_bf16_f32 v18, v13, v15
	v_mul_f32_e32 v13, v19, v23
	v_mul_f32_e32 v15, v19, v22
	v_mul_f32_e32 v13, v8, v13
	v_mul_f32_e32 v15, v9, v15
	v_cvt_pk_bf16_f32 v19, v13, v15
	global_store_dwordx4 v[20:21], v[16:19], off offset:512
	s_andn2_b64 exec, exec, s[2:3]
	s_cbranch_execnz .LBB0_4071

; template <int D> __device__ __forceinline__ void head_vec8(const bf16_t* __restrict__ src, const float* __restrict__ gain, bool norm, bool rope, float scale,
;                                                            const f32x2* __restrict__ cs, bf16_t* __restrict__ dst, const int sub) {
;     constexpr int NH = D / 16;
;     float lo[NH], hi[NH];
;     if (NH == 4) {
;         const u32x2 a = *(const u32x2*)(src + sub * 4), b = *(const u32x2*)(src + D / 2 + sub * 4);
;         lo[0] = bf2f(a.x & 0xffffu); lo[1] = bf2f(a.x >> 16); lo[NH - 2] = bf2f(a.y & 0xffffu); lo[NH - 1] = bf2f(a.y >> 16);
;         hi[0] = bf2f(b.x & 0xffffu); hi[1] = bf2f(b.x >> 16); hi[NH - 2] = bf2f(b.y & 0xffffu); hi[NH - 1] = bf2f(b.y >> 16);
;     } else {
;         const unsigned a = *(const unsigned*)(src + sub * 2), b = *(const unsigned*)(src + D / 2 + sub * 2);
;         lo[0] = bf2f(a & 0xffffu); lo[1] = bf2f(a >> 16); hi[0] = bf2f(b & 0xffffu); hi[1] = bf2f(b >> 16);
;     }
;     float ss = 0.f;
; #pragma unroll
;     for (int i = 0; i < NH; ++i) ss += lo[i] * lo[i] + hi[i] * hi[i];
;     ss += __shfl_xor(ss, 1); ss += __shfl_xor(ss, 2); ss += __shfl_xor(ss, 4);
;     const float rs = norm ? __builtin_amdgcn_rsqf(ss * (1.0f / D) + EPS) : 1.0f;
;     float cc[NH], sn[NH];
;     if (NH == 4) {
;         const f32x4 g0 = *(const f32x4*)(gain + sub * 4), g1 = *(const f32x4*)(gain + D / 2 + sub * 4);
;         const f32x4 c0 = *(const f32x4*)(cs + sub * 4), c1 = *(const f32x4*)(cs + sub * 4 + 2);
; #pragma unroll
;         for (int i = 0; i < 4; ++i) { lo[i] *= norm ? rs * g0[i] : 1.0f; hi[i] *= norm ? rs * g1[i] : 1.0f; }
;         cc[0] = c0[0]; sn[0] = c0[1]; cc[1] = c0[2]; sn[1] = c0[3]; cc[NH - 2] = c1[0]; sn[NH - 2] = c1[1]; cc[NH - 1] = c1[2]; sn[NH - 1] = c1[3];
;     } else {
;         const f32x2 g0 = *(const f32x2*)(gain + sub * 2), g1 = *(const f32x2*)(gain + D / 2 + sub * 2);
;         const f32x4 c0 = *(const f32x4*)(cs + sub * 2);
; #pragma unroll
; __global__ void __launch_bounds__(512, 2) mega_fwd(KArgs a) {
;     ...
;             for (int e = gw * 64 + lane; e < T_ * 8; e += NGW * 64) {
;                 const int t = e >> 3;
;                 head_vec8<32>(RA + (size_t)t * EVEN_INP + 384, mkg + 64, true, true, 1.0f, CS32 + (size_t)t * 16, KROPE + (size_t)t * 32, lane & 7);
;             }
.LBB0_4074:
	v_ashrrev_i32_e32 v16, 3, v12
	v_mov_b64_e32 v[18:19], s[4:5]
	v_ashrrev_i32_e32 v17, 31, v16
	v_mad_i64_i32 v[18:19], s[14:15], v16, s96, v[18:19]
	v_mov_b32_e32 v11, v0
	v_lshlrev_b64 v[20:21], 7, v[16:17]
	s_waitcnt vmcnt(5)
	v_lshlrev_b64 v[22:23], 6, v[16:17]
	v_lshl_add_u64 v[16:17], v[18:19], 0, v[10:11]
	v_add_co_u32_e32 v16, vcc, 0x8c00000, v16
	s_nop 1
	v_addc_co_u32_e32 v17, vcc, 0, v17, vcc
	global_load_dword v11, v[16:17], off offset:768
	global_load_dword v13, v[16:17], off offset:800
	v_cmp_lt_i32_e32 vcc, -1, v12
	s_or_b64 s[12:13], vcc, s[12:13]
	s_waitcnt vmcnt(1)
	v_lshlrev_b32_e32 v15, 16, v11
	s_waitcnt vmcnt(0)
	v_lshlrev_b32_e32 v24, 16, v13
	v_and_b32_e32 v13, 0xffff0000, v13
	v_and_b32_e32 v11, 0xffff0000, v11
	v_mul_f32_e32 v16, v24, v24
	v_mul_f32_e32 v17, v13, v13
	v_fmac_f32_e32 v16, v15, v15
	v_fmac_f32_e32 v17, v11, v11
	v_add_f32_e32 v16, v16, v17
	s_nop 1
	v_mov_b32_dpp v17, v16 quad_perm:[1,0,3,2] row_mask:0xf bank_mask:0xf
	s_waitcnt lgkmcnt(0)
	v_add_f32_e32 v16, v16, v17
	s_nop 1
	v_mov_b32_dpp v17, v16 quad_perm:[2,3,0,1] row_mask:0xf bank_mask:0xf
	s_waitcnt lgkmcnt(0)
	v_add_f32_e32 v16, v16, v17
	s_nop 1
	v_mov_b32_dpp v17, v16 row_shl:4 row_mask:0xf bank_mask:0x5
	v_mov_b32_dpp v17, v16 row_shr:4 row_mask:0xf bank_mask:0xa
	s_waitcnt lgkmcnt(0)
	v_add_f32_e32 v16, v16, v17
	v_fmamk_f32 v16, v16, 0x3d000000, v231
	v_rsq_f32_e32 v25, v16
	v_lshl_add_u64 v[16:17], v[6:7], 0, v[20:21]
	global_load_dwordx4 v[16:19], v[16:17], off
	v_mul_f32_e32 v20, v2, v25
	v_mul_f32_e32 v15, v20, v15
	v_mul_f32_e32 v20, v4, v25
	v_mul_f32_e32 v21, v3, v25
	v_mul_f32_e32 v20, v20, v24
	v_mul_f32_e32 v11, v21, v11
	v_mul_f32_e32 v21, v5, v25
	v_mul_f32_e32 v13, v21, v13
	s_waitcnt vmcnt(0)
	v_mul_f32_e32 v21, v17, v20
	v_fma_f32 v21, v16, v15, -v21
	v_mul_f32_e32 v15, v17, v15
	v_fmac_f32_e32 v15, v16, v20
	v_mul_f32_e32 v16, v19, v13
	v_fma_f32 v16, v18, v11, -v16
	v_mul_f32_e32 v11, v19, v11
	v_fmac_f32_e32 v11, v18, v13
	v_cvt_pk_bf16_f32 v13, v21, v16
	v_lshl_add_u64 v[16:17], v[8:9], 0, v[22:23]
	global_store_dword v[16:17], v13, off
	v_cvt_pk_bf16_f32 v11, v15, v11
	global_store_dword v[16:17], v11, off offset:32
	v_add_u32_e32 v11, 0x20000, v12
	v_mov_b32_e32 v12, v11
	s_andn2_b64 exec, exec, s[12:13]
	s_cbranch_execnz .LBB0_4074

; template <int D> __device__ __forceinline__ void hv_load(HVRaw& r, const bf16_t* __restrict__ src, const float* __restrict__ gain, const f32x2* __restrict__ cs, const int sub) {
;     if (D == 64) {
;         r.a = *(const u32x2*)(src + sub * 4); r.b = *(const u32x2*)(src + 32 + sub * 4);
;         r.g0 = *(const f32x4*)(gain + sub * 4); r.g1 = *(const f32x4*)(gain + 32 + sub * 4);
;         r.c0 = *(const f32x4*)(cs + sub * 4); r.c1 = *(const f32x4*)(cs + sub * 4 + 2);
;     } else {
;         r.a.x = *(const unsigned*)(src + sub * 2); r.b.x = *(const unsigned*)(src + 16 + sub * 2); r.a.y = 0u; r.b.y = 0u;
;         const f32x2 g0 = *(const f32x2*)(gain + sub * 2), g1 = *(const f32x2*)(gain + 16 + sub * 2);
;         r.g0 = (f32x4){g0.x, g0.y, 0.f, 0.f}; r.g1 = (f32x4){g1.x, g1.y, 0.f, 0.f};
;         r.c0 = *(const f32x4*)(cs + sub * 2); r.c1 = r.c0;
;     }
; }
; __global__ void __launch_bounds__(512, 2) mega_fwd(KArgs a) {
;     ...
;             for (int e0 = gw * 64 + lane; e0 < T_ * 24 * 8; e0 += NGW * 64 * 4) {
;                 HVRaw hr[4]; bf16_t* dsts[4]; bool isk[4];
; #pragma unroll
;                 for (int u4 = 0; u4 < 4; ++u4) {
;                     const int ev = (e0 + u4 * NGW * 64) >> 3, t = ev / 24, gq = ev - t * 24, g = gq >> 3, qk = (gq >> 2) & 1, h = gq & 3, b = t >> 11, sq = t & 2047;
;                     const int sh = (g == 0) ? 0 : (g == 1) ? 2 : 4;
;                     const int pi = ((sq & ((1 << sh) - 1)) << (11 - sh)) + (sq >> sh);
;                     dsts[u4] = (qk ? KD : QD) + ((size_t)((b * 3 + g) * 4 + h) * 2048 + pi) * 64; isk[u4] = qk != 0;
;                     hv_load<64>(hr[u4], RA + (size_t)t * EVEN_INP + 416 + ((g * 3 + qk) * 4 + h) * 64, qk ? dkg : dqg, CS64 + (size_t)t * 32, lane & 7);
;                 }
.LBB0_4077:
	v_ashrrev_i32_e32 v74, 3, v1
	v_mul_hi_i32 v2, v74, s72
	v_lshrrev_b32_e32 v3, 31, v2
	v_ashrrev_i32_e32 v2, 2, v2
	v_add_u32_e32 v2, v2, v3
	v_mad_u64_u32 v[4:5], s[16:17], v2, s35, v[74:75]
	v_ashrrev_i32_e32 v7, 3, v4
	v_cmp_eq_u32_e32 vcc, 1, v7
	v_ashrrev_i32_e32 v3, 11, v2
	v_bfe_u32 v6, v74, 2, 1
	v_cndmask_b32_e64 v8, 4, 2, vcc
	v_cmp_lt_u32_e32 vcc, 7, v4
	v_and_b32_e32 v12, 3, v74
	v_mad_i32_i24 v3, v3, 3, v7
	v_cndmask_b32_e32 v4, 0, v8, vcc
	v_and_b32_e32 v5, 0x7ff, v2
	v_sub_u32_e32 v8, 11, v4
	v_cmp_eq_u32_e32 vcc, 0, v6
	v_lshl_or_b32 v10, v3, 2, v12
	v_lshlrev_b32_e32 v8, v8, v2
	v_lshrrev_b32_e32 v14, v4, v5
	v_cndmask_b32_e32 v4, v239, v240, vcc
	v_mov_b32_e32 v5, v0
	v_ashrrev_i32_e32 v11, 31, v10
	v_mad_u64_u32 v[6:7], s[16:17], v7, 3, v[6:7]
	v_and_b32_e32 v13, 0x7fe, v8
	v_lshl_add_u64 v[4:5], s[10:11], 0, v[4:5]
	v_lshlrev_b64 v[10:11], 18, v[10:11]
	v_lshlrev_b32_e32 v7, 6, v12
	v_lshl_add_u64 v[4:5], v[4:5], 0, v[10:11]
	v_add_lshl_u32 v10, v13, v14, 7
	v_mov_b32_e32 v11, v0
	v_mov_b64_e32 v[50:51], s[10:11]
	v_lshl_or_b32 v6, v6, 8, v7
	v_lshl_add_u64 v[76:77], v[4:5], 0, v[10:11]
	v_mad_i64_i32 v[4:5], s[16:17], v2, s96, v[50:51]
	v_ashrrev_i32_e32 v7, 31, v6
	v_mov_b32_e32 v54, s9
	v_mov_b32_e32 v55, s7
	v_mov_b32_e32 v56, s8
	v_mov_b32_e32 v57, s6
	v_lshl_add_u64 v[4:5], v[6:7], 1, v[4:5]
	v_lshlrev_b32_e32 v72, 1, v68
	v_mov_b32_e32 v73, v0
	v_cndmask_b32_e32 v9, v54, v55, vcc
	v_cndmask_b32_e32 v8, v56, v57, vcc
	v_lshl_add_u64 v[4:5], v[4:5], 0, v[72:73]
	v_lshl_add_u64 v[6:7], v[8:9], 0, s[14:15]
	v_lshl_add_u64 v[8:9], v[4:5], 0, s[36:37]
	v_add_co_u32_e32 v4, vcc, s76, v4
	v_lshlrev_b32_e32 v52, 2, v68
	s_nop 0
	v_addc_co_u32_e32 v5, vcc, 0, v5, vcc
	v_mov_b32_e32 v53, v0
	global_load_dwordx2 v[78:79], v[4:5], off offset:832
	global_load_dwordx2 v[80:81], v[8:9], off offset:64
	v_lshl_add_u64 v[4:5], v[6:7], 0, v[52:53]
	global_load_dwordx4 v[10:13], v[4:5], off
	global_load_dwordx4 v[14:17], v[4:5], off offset:128
	v_add_u32_e32 v18, 0x20000, v1
	v_ashrrev_i32_e32 v3, 31, v2
	v_ashrrev_i32_e32 v82, 3, v18
	v_lshlrev_b64 v[2:3], 8, v[2:3]
	v_mul_hi_i32 v18, v82, s72
	v_lshl_add_u64 v[6:7], v[70:71], 0, v[2:3]
	v_lshrrev_b32_e32 v19, 31, v18
	v_ashrrev_i32_e32 v18, 2, v18
	global_load_dwordx4 v[2:5], v[6:7], off offset:16
	s_nop 0
	global_load_dwordx4 v[6:9], v[6:7], off
	v_add_u32_e32 v18, v18, v19
	v_mad_u64_u32 v[20:21], s[16:17], v18, s35, v[82:83]
	s_waitcnt vmcnt(9)
	v_ashrrev_i32_e32 v23, 3, v20
	v_cmp_eq_u32_e32 vcc, 1, v23
	v_ashrrev_i32_e32 v19, 11, v18
	v_bfe_u32 v22, v82, 2, 1
	v_cndmask_b32_e64 v24, 4, 2, vcc
	v_cmp_lt_u32_e32 vcc, 7, v20
	s_waitcnt vmcnt(8)
	v_and_b32_e32 v28, 3, v82
	v_mad_i32_i24 v19, v19, 3, v23
	v_cndmask_b32_e32 v20, 0, v24, vcc
	v_and_b32_e32 v21, 0x7ff, v18
	v_sub_u32_e32 v24, 11, v20
	v_cmp_eq_u32_e32 vcc, 0, v22
	v_lshl_or_b32 v26, v19, 2, v28
	v_lshlrev_b32_e32 v24, v24, v18
	v_lshrrev_b32_e32 v30, v20, v21
	v_cndmask_b32_e32 v20, v239, v240, vcc
	v_mov_b32_e32 v21, v0
	v_ashrrev_i32_e32 v27, 31, v26
	v_mad_u64_u32 v[22:23], s[16:17], v23, 3, v[22:23]
	v_and_b32_e32 v29, 0x7fe, v24
	v_lshl_add_u64 v[20:21], s[10:11], 0, v[20:21]
	v_lshlrev_b64 v[26:27], 18, v[26:27]
	v_lshlrev_b32_e32 v23, 6, v28
	v_lshl_add_u64 v[20:21], v[20:21], 0, v[26:27]
	v_add_lshl_u32 v26, v29, v30, 7
	v_mov_b32_e32 v27, v0
	v_lshl_or_b32 v22, v22, 8, v23
	v_lshl_add_u64 v[84:85], v[20:21], 0, v[26:27]
	v_mad_i64_i32 v[20:21], s[16:17], v18, s96, v[50:51]
	v_ashrrev_i32_e32 v23, 31, v22
	v_lshl_add_u64 v[20:21], v[22:23], 1, v[20:21]
	v_cndmask_b32_e32 v25, v54, v55, vcc
	v_cndmask_b32_e32 v24, v56, v57, vcc
	v_lshl_add_u64 v[20:21], v[20:21], 0, v[72:73]
	v_lshl_add_u64 v[22:23], v[24:25], 0, s[14:15]
	v_lshl_add_u64 v[24:25], v[20:21], 0, s[36:37]
	v_add_co_u32_e32 v20, vcc, s76, v20
	v_add_u32_e32 v34, 0x40000, v1
	s_nop 0
	v_addc_co_u32_e32 v21, vcc, 0, v21, vcc
	global_load_dwordx2 v[86:87], v[20:21], off offset:832
	global_load_dwordx2 v[88:89], v[24:25], off offset:64
	v_lshl_add_u64 v[20:21], v[22:23], 0, v[52:53]
	global_load_dwordx4 v[26:29], v[20:21], off
	global_load_dwordx4 v[30:33], v[20:21], off offset:128
	v_ashrrev_i32_e32 v90, 3, v34
	v_mul_hi_i32 v34, v90, s72
	v_lshrrev_b32_e32 v35, 31, v34
	v_ashrrev_i32_e32 v34, 2, v34
	v_add_u32_e32 v34, v34, v35
	v_mad_u64_u32 v[36:37], s[16:17], v34, s35, v[90:91]
	v_ashrrev_i32_e32 v39, 3, v36
	v_cmp_eq_u32_e32 vcc, 1, v39
	v_ashrrev_i32_e32 v35, 11, v34
	v_bfe_u32 v38, v90, 2, 1
	v_cndmask_b32_e64 v40, 4, 2, vcc
	v_cmp_lt_u32_e32 vcc, 7, v36
	v_and_b32_e32 v44, 3, v90
	v_mad_i32_i24 v35, v35, 3, v39
	v_cndmask_b32_e32 v36, 0, v40, vcc
	v_and_b32_e32 v37, 0x7ff, v34
	v_sub_u32_e32 v40, 11, v36
	v_cmp_eq_u32_e32 vcc, 0, v38
	v_lshl_or_b32 v42, v35, 2, v44
	v_lshlrev_b32_e32 v40, v40, v34
	v_lshrrev_b32_e32 v46, v36, v37
	v_cndmask_b32_e32 v36, v239, v240, vcc
	v_mov_b32_e32 v37, v0
	v_ashrrev_i32_e32 v43, 31, v42
	v_mad_u64_u32 v[38:39], s[16:17], v39, 3, v[38:39]
	v_and_b32_e32 v45, 0x7fe, v40
	v_lshl_add_u64 v[36:37], s[10:11], 0, v[36:37]
	v_lshlrev_b64 v[42:43], 18, v[42:43]
	v_lshlrev_b32_e32 v39, 6, v44
	v_add_u32_e32 v58, 0x60000, v1
	v_lshl_add_u64 v[36:37], v[36:37], 0, v[42:43]
	v_add_lshl_u32 v42, v45, v46, 7
	v_mov_b32_e32 v43, v0
	v_lshl_or_b32 v38, v38, 8, v39
	v_ashrrev_i32_e32 v98, 3, v58
	v_lshl_add_u64 v[92:93], v[36:37], 0, v[42:43]
	v_mad_i64_i32 v[36:37], s[16:17], v34, s96, v[50:51]
	v_ashrrev_i32_e32 v39, 31, v38
	v_mul_hi_i32 v58, v98, s72
	v_lshl_add_u64 v[36:37], v[38:39], 1, v[36:37]
	v_lshrrev_b32_e32 v59, 31, v58
	v_ashrrev_i32_e32 v58, 2, v58
	v_cndmask_b32_e32 v41, v54, v55, vcc
	v_cndmask_b32_e32 v40, v56, v57, vcc
	v_lshl_add_u64 v[36:37], v[36:37], 0, v[72:73]
	v_add_u32_e32 v58, v58, v59
	v_lshl_add_u64 v[38:39], v[40:41], 0, s[14:15]
	v_lshl_add_u64 v[40:41], v[36:37], 0, s[36:37]
	v_add_co_u32_e32 v36, vcc, s76, v36
	v_mad_u64_u32 v[60:61], s[16:17], v58, s35, v[98:99]
	s_nop 0
	v_addc_co_u32_e32 v37, vcc, 0, v37, vcc
	v_ashrrev_i32_e32 v63, 3, v60
	v_cmp_eq_u32_e32 vcc, 1, v63
	v_bfe_u32 v62, v98, 2, 1
	v_ashrrev_i32_e32 v59, 11, v58
	v_cndmask_b32_e64 v65, 4, 2, vcc
	v_cmp_lt_u32_e32 vcc, 7, v60
	v_and_b32_e32 v61, 0x7ff, v58
	v_and_b32_e32 v64, 3, v98
	v_cndmask_b32_e32 v60, 0, v65, vcc
	v_cmp_eq_u32_e32 vcc, 0, v62
	v_sub_u32_e32 v65, 11, v60
	v_lshrrev_b32_e32 v67, v60, v61
	v_cndmask_b32_e32 v60, v239, v240, vcc
	v_mov_b32_e32 v61, v0
	v_mad_i32_i24 v59, v59, 3, v63
	v_cndmask_b32_e32 v55, v54, v55, vcc
	v_cndmask_b32_e32 v54, v56, v57, vcc
	v_lshl_add_u64 v[56:57], s[10:11], 0, v[60:61]
	v_lshl_or_b32 v60, v59, 2, v64
	v_ashrrev_i32_e32 v19, 31, v18
	v_lshlrev_b32_e32 v65, v65, v58
	v_ashrrev_i32_e32 v61, 31, v60
	v_lshlrev_b64 v[18:19], 8, v[18:19]
	v_and_b32_e32 v65, 0x7fe, v65
	v_lshlrev_b64 v[60:61], 18, v[60:61]
	s_waitcnt vmcnt(9)
; template <int D> __device__ __forceinline__ void hv_finish(const HVRaw& r, bool norm, bool rope, float scale, bf16_t* __restrict__ dst, const int sub) {
;     constexpr int NH = D / 16;
;     float lo[4], hi[4], cc[4], sn[4];
;     lo[0] = bf2f(r.a.x & 0xffffu); lo[1] = bf2f(r.a.x >> 16); lo[2] = bf2f(r.a.y & 0xffffu); lo[3] = bf2f(r.a.y >> 16);
;     hi[0] = bf2f(r.b.x & 0xffffu); hi[1] = bf2f(r.b.x >> 16); hi[2] = bf2f(r.b.y & 0xffffu); hi[3] = bf2f(r.b.y >> 16);
;     float ss = 0.f;
; #pragma unroll
;     for (int i = 0; i < NH; ++i) ss += lo[i] * lo[i] + hi[i] * hi[i];
;     ss += __shfl_xor(ss, 1); ss += __shfl_xor(ss, 2); ss += __shfl_xor(ss, 4);
;     const float rs = norm ? __builtin_amdgcn_rsqf(ss * (1.0f / D) + EPS) : 1.0f;
; #pragma unroll
;     for (int i = 0; i < NH; ++i) { lo[i] *= norm ? rs * r.g0[i] : 1.0f; hi[i] *= norm ? rs * r.g1[i] : 1.0f; }
;     cc[0] = r.c0[0]; sn[0] = r.c0[1]; cc[1] = r.c0[2]; sn[1] = r.c0[3]; cc[2] = r.c1[0]; sn[2] = r.c1[1]; cc[3] = r.c1[2]; sn[3] = r.c1[3];
;     float ol[4], oh[4];
; #pragma unroll
;     for (int i = 0; i < NH; ++i) {
;         const float c = rope ? cc[i] : 1.0f, sv = rope ? sn[i] : 0.0f;
;         ol[i] = (lo[i] * c - hi[i] * sv) * scale; oh[i] = (hi[i] * c + lo[i] * sv) * scale;
;     }
;     if (NH == 4) {
;         u32x2 w0, w1; w0.x = pg8::cvt_pk_bf16(ol[0], ol[1]); w0.y = pg8::cvt_pk_bf16(ol[2], ol[3]); w1.x = pg8::cvt_pk_bf16(oh[0], oh[1]); w1.y = pg8::cvt_pk_bf16(oh[2], oh[3]);
; __global__ void __launch_bounds__(512, 2) mega_fwd(KArgs a) {
;     ...
;                 for (int u4 = 0; u4 < 4; ++u4) {
;                     const int ev = (e0 + u4 * NGW * 64) >> 3, t = ev / 24, gq = ev - t * 24, g = gq >> 3, qk = (gq >> 2) & 1, h = gq & 3, b = t >> 11, sq = t & 2047;
;                     const int sh = (g == 0) ? 0 : (g == 1) ? 2 : 4;
;                     const int pi = ((sq & ((1 << sh) - 1)) << (11 - sh)) + (sq >> sh);
;                     dsts[u4] = (qk ? KD : QD) + ((size_t)((b * 3 + g) * 4 + h) * 2048 + pi) * 64; isk[u4] = qk != 0;
;                     hv_load<64>(hr[u4], RA + (size_t)t * EVEN_INP + 416 + ((g * 3 + qk) * 4 + h) * 64, qk ? dkg : dqg, CS64 + (size_t)t * 32, lane & 7);
;                 }
; #pragma unroll
;                 for (int u4 = 0; u4 < 4; ++u4) hv_finish<64>(hr[u4], true, true, isk[u4] ? 1.0f : 0.125f * LOG2E, dsts[u4], lane & 7);
	v_lshlrev_b32_e32 v75, 16, v79
	s_waitcnt vmcnt(6)
	v_mov_b32_e32 v106, v16
	v_mov_b32_e32 v107, v12
	v_and_b32_e32 v109, 0xffff0000, v79
	v_mov_b32_e32 v12, v17
	v_lshlrev_b32_e32 v17, 16, v78
	v_lshlrev_b32_e32 v16, 16, v80
	v_and_b32_e32 v79, 0xffff0000, v78
	v_and_b32_e32 v78, 0xffff0000, v80
	v_lshl_add_u64 v[22:23], v[70:71], 0, v[18:19]
	v_lshl_add_u64 v[56:57], v[56:57], 0, v[60:61]
	v_add_lshl_u32 v60, v65, v67, 7
	v_and_b32_e32 v67, 4, v74
	v_lshlrev_b32_e32 v74, 16, v81
	v_and_b32_e32 v108, 0xffff0000, v81
	v_mov_b32_e32 v114, v16
	v_mov_b32_e32 v115, v78
	global_load_dwordx4 v[18:21], v[22:23], off offset:16
	s_nop 0
	global_load_dwordx4 v[22:25], v[22:23], off
	v_mov_b32_e32 v112, v108
	v_mov_b32_e32 v113, v74
	v_mov_b32_e32 v80, v17
	v_mov_b32_e32 v81, v79
	v_pk_mul_f32 v[114:115], v[114:115], v[114:115]
	v_mov_b32_e32 v110, v109
	v_mov_b32_e32 v111, v75
	v_pk_mul_f32 v[112:113], v[112:113], v[112:113]
	v_pk_fma_f32 v[80:81], v[80:81], v[80:81], v[114:115]
	v_pk_fma_f32 v[110:111], v[110:111], v[110:111], v[112:113]
	v_mov_b32_e32 v113, v10
	v_add_f32_e32 v10, v80, v81
	v_add_f32_e32 v10, v111, v10
	v_add_f32_e32 v10, v110, v10
	v_mov_b32_e32 v112, v14
	s_nop 1
	v_mov_b32_dpp v14, v10 quad_perm:[1,0,3,2] row_mask:0xf bank_mask:0xf
	global_load_dwordx2 v[94:95], v[36:37], off offset:832
	global_load_dwordx2 v[96:97], v[40:41], off offset:64
	v_mov_b32_e32 v61, v0
	v_lshl_add_u64 v[100:101], v[56:57], 0, v[60:61]
	v_mad_u64_u32 v[56:57], s[16:17], v63, 3, v[62:63]
	s_waitcnt lgkmcnt(0)
	v_add_f32_e32 v10, v10, v14
	s_nop 1
	v_mov_b32_dpp v14, v10 quad_perm:[2,3,0,1] row_mask:0xf bank_mask:0xf
	v_lshlrev_b32_e32 v57, 6, v64
	v_lshl_or_b32 v56, v56, 8, v57
	v_mad_i64_i32 v[50:51], s[16:17], v58, s96, v[50:51]
	s_waitcnt lgkmcnt(0)
	v_add_f32_e32 v10, v10, v14
	s_nop 1
	v_mov_b32_dpp v14, v10 row_shl:4 row_mask:0xf bank_mask:0x5
	v_mov_b32_dpp v14, v10 row_shr:4 row_mask:0xf bank_mask:0xa
	v_ashrrev_i32_e32 v57, 31, v56
	v_lshl_add_u64 v[50:51], v[56:57], 1, v[50:51]
	v_ashrrev_i32_e32 v59, 31, v58
	v_lshl_add_u64 v[50:51], v[50:51], 0, v[72:73]
	s_waitcnt lgkmcnt(0)
	v_add_f32_e32 v10, v10, v14
	v_fmamk_f32 v10, v10, 0x3c800000, v231
	v_rsq_f32_e32 v14, v10
	v_lshlrev_b64 v[56:57], 8, v[58:59]
	v_lshl_add_u64 v[58:59], v[50:51], 0, s[36:37]
	v_add_co_u32_e32 v50, vcc, s76, v50
	v_pk_mul_f32 v[80:81], v[112:113], v[14:15] op_sel_hi:[1,0]
	v_mov_b32_e32 v10, v15
	v_addc_co_u32_e32 v51, vcc, 0, v51, vcc
	v_pk_mul_f32 v[16:17], v[80:81], v[16:17]
	v_pk_mul_f32 v[10:11], v[10:11], v[14:15] op_sel_hi:[1,0]
	v_cmp_ne_u32_e32 vcc, 0, v67
	v_pk_mul_f32 v[10:11], v[10:11], v[78:79]
	v_pk_mul_f32 v[78:79], v[106:107], v[14:15] op_sel_hi:[1,0]
	v_pk_mul_f32 v[12:13], v[12:13], v[14:15] op_sel_hi:[1,0]
	s_waitcnt vmcnt(8)
	v_pk_mul_f32 v[14:15], v[6:7], v[16:17] op_sel:[0,1] op_sel_hi:[1,0]
	v_pk_mul_f32 v[6:7], v[6:7], v[16:17]
	v_cndmask_b32_e64 v67, v237, 1.0, vcc
	v_add_f32_e32 v6, v6, v7
	v_sub_f32_e32 v14, v14, v15
	v_mul_f32_e32 v15, v67, v6
	v_pk_mul_f32 v[6:7], v[8:9], v[10:11] op_sel:[0,1] op_sel_hi:[1,0]
	v_pk_mul_f32 v[74:75], v[78:79], v[74:75]
	v_sub_f32_e32 v6, v6, v7
	v_mul_f32_e32 v16, v67, v6
	v_pk_mul_f32 v[6:7], v[8:9], v[10:11]
	v_pk_mul_f32 v[12:13], v[12:13], v[108:109]
	v_add_f32_e32 v6, v6, v7
	v_mul_f32_e32 v8, v67, v6
	v_pk_mul_f32 v[6:7], v[2:3], v[74:75] op_sel:[0,1] op_sel_hi:[1,0]
	v_pk_mul_f32 v[2:3], v[2:3], v[74:75]
	v_sub_f32_e32 v6, v6, v7
	v_add_f32_e32 v2, v2, v3
	v_mul_f32_e32 v7, v67, v2
	v_pk_mul_f32 v[2:3], v[4:5], v[12:13] op_sel:[0,1] op_sel_hi:[1,0]
	v_ashrrev_i32_e32 v35, 31, v34
	v_sub_f32_e32 v2, v2, v3
	v_lshlrev_b64 v[34:35], 8, v[34:35]
	v_mul_f32_e32 v9, v67, v2
	v_pk_mul_f32 v[2:3], v[4:5], v[12:13]
	v_lshl_add_u64 v[36:37], v[38:39], 0, v[52:53]
	v_lshl_add_u64 v[38:39], v[70:71], 0, v[34:35]
	v_lshl_add_u64 v[54:55], v[54:55], 0, s[14:15]
	v_add_f32_e32 v2, v2, v3
	global_load_dwordx4 v[42:45], v[36:37], off
	global_load_dwordx4 v[46:49], v[36:37], off offset:128
	s_nop 0
	global_load_dwordx4 v[34:37], v[38:39], off offset:16
	s_nop 0
	global_load_dwordx4 v[38:41], v[38:39], off
	s_nop 0
	global_load_dwordx2 v[102:103], v[50:51], off offset:832
	global_load_dwordx2 v[104:105], v[58:59], off offset:64
	v_lshl_add_u64 v[50:51], v[54:55], 0, v[52:53]
	v_lshl_add_u64 v[54:55], v[70:71], 0, v[56:57]
	v_mul_f32_e32 v6, v67, v6
	v_mul_f32_e32 v5, v67, v2
	global_load_dwordx4 v[58:61], v[50:51], off
	global_load_dwordx4 v[62:65], v[50:51], off offset:128
	s_nop 0
	global_load_dwordx4 v[50:53], v[54:55], off offset:16
	s_nop 0
	global_load_dwordx4 v[54:57], v[54:55], off
	v_mul_f32_e32 v14, v67, v14
	v_cvt_pk_bf16_f32 v2, v14, v16
	v_cvt_pk_bf16_f32 v3, v6, v9
	v_cvt_pk_bf16_f32 v4, v15, v8
	v_cvt_pk_bf16_f32 v5, v7, v5
	v_lshl_add_u64 v[6:7], v[76:77], 0, v[72:73]
	global_store_dwordx2 v[6:7], v[2:3], off
	global_store_dwordx2 v[6:7], v[4:5], off offset:64
	v_and_b32_e32 v2, 4, v82
	v_cmp_ne_u32_e32 vcc, 0, v2
	s_waitcnt vmcnt(18)
	v_lshlrev_b32_e32 v2, 16, v89
	v_and_b32_e32 v6, 0xffff0000, v89
	v_lshlrev_b32_e32 v3, 16, v87
	v_and_b32_e32 v7, 0xffff0000, v87
	v_mov_b32_e32 v10, v6
	v_mov_b32_e32 v11, v2
	v_mov_b32_e32 v8, v7
	v_mov_b32_e32 v9, v3
	v_pk_mul_f32 v[10:11], v[10:11], v[10:11]
	v_and_b32_e32 v14, 0xffff0000, v88
	v_pk_fma_f32 v[8:9], v[8:9], v[8:9], v[10:11]
	v_lshlrev_b32_e32 v10, 16, v88
	s_waitcnt vmcnt(16)
; __device__ __forceinline__ unsigned cvt_pk_bf16(float lo, float hi) { unsigned r; asm volatile("v_cvt_pk_bf16_f32 %0, %1, %2" : "=v"(r) : "v"(lo), "v"(hi)); return r; }
; __device__ __forceinline__ float bf2f(unsigned h) { return __uint_as_float(h << 16); }
; template <int D> __device__ __forceinline__ void hv_finish(const HVRaw& r, bool norm, bool rope, float scale, bf16_t* __restrict__ dst, const int sub) {
;     constexpr int NH = D / 16;
;     float lo[4], hi[4], cc[4], sn[4];
;     lo[0] = bf2f(r.a.x & 0xffffu); lo[1] = bf2f(r.a.x >> 16); lo[2] = bf2f(r.a.y & 0xffffu); lo[3] = bf2f(r.a.y >> 16);
;     hi[0] = bf2f(r.b.x & 0xffffu); hi[1] = bf2f(r.b.x >> 16); hi[2] = bf2f(r.b.y & 0xffffu); hi[3] = bf2f(r.b.y >> 16);
;     float ss = 0.f;
; #pragma unroll
;     for (int i = 0; i < NH; ++i) ss += lo[i] * lo[i] + hi[i] * hi[i];
;     ss += __shfl_xor(ss, 1); ss += __shfl_xor(ss, 2); ss += __shfl_xor(ss, 4);
;     const float rs = norm ? __builtin_amdgcn_rsqf(ss * (1.0f / D) + EPS) : 1.0f;
; #pragma unroll
;     for (int i = 0; i < NH; ++i) { lo[i] *= norm ? rs * r.g0[i] : 1.0f; hi[i] *= norm ? rs * r.g1[i] : 1.0f; }
;     cc[0] = r.c0[0]; sn[0] = r.c0[1]; cc[1] = r.c0[2]; sn[1] = r.c0[3]; cc[2] = r.c1[0]; sn[2] = r.c1[1]; cc[3] = r.c1[2]; sn[3] = r.c1[3];
;     float ol[4], oh[4];
; #pragma unroll
;     for (int i = 0; i < NH; ++i) {
;         const float c = rope ? cc[i] : 1.0f, sv = rope ? sn[i] : 0.0f;
;         ol[i] = (lo[i] * c - hi[i] * sv) * scale; oh[i] = (hi[i] * c + lo[i] * sv) * scale;
;     }
;     if (NH == 4) {
;         u32x2 w0, w1; w0.x = pg8::cvt_pk_bf16(ol[0], ol[1]); w0.y = pg8::cvt_pk_bf16(ol[2], ol[3]); w1.x = pg8::cvt_pk_bf16(oh[0], oh[1]); w1.y = pg8::cvt_pk_bf16(oh[2], oh[3]);
;         *(u32x2*)(dst + sub * 4) = w0; *(u32x2*)(dst + 32 + sub * 4) = w1;
;     } else {
;         *(unsigned*)(dst + sub * 2) = pg8::cvt_pk_bf16(ol[0], ol[1]); *(unsigned*)(dst + 16 + sub * 2) = pg8::cvt_pk_bf16(oh[0], oh[1]);
;     }
; }
	v_mov_b32_e32 v4, v32
	v_mov_b32_e32 v5, v28
	v_mov_b32_e32 v28, v33
	v_lshlrev_b32_e32 v11, 16, v86
	v_and_b32_e32 v15, 0xffff0000, v86
	v_mov_b32_e32 v32, v10
	v_mov_b32_e32 v33, v14
	v_mov_b32_e32 v16, v11
	v_mov_b32_e32 v17, v15
	v_pk_mul_f32 v[32:33], v[32:33], v[32:33]
	v_mov_b32_e32 v12, v30
	v_pk_fma_f32 v[16:17], v[16:17], v[16:17], v[32:33]
	v_mov_b32_e32 v13, v26
	v_add_f32_e32 v16, v16, v17
	v_add_f32_e32 v9, v9, v16
	v_add_f32_e32 v8, v8, v9
	s_nop 1
	v_mov_b32_dpp v9, v8 quad_perm:[1,0,3,2] row_mask:0xf bank_mask:0xf
	v_cndmask_b32_e64 v67, v237, 1.0, vcc
	v_mov_b32_e32 v26, v31
	s_mov_b32 s16, 0x27ffff
	s_waitcnt lgkmcnt(0)
	v_add_f32_e32 v8, v8, v9
	s_nop 1
	v_mov_b32_dpp v9, v8 quad_perm:[2,3,0,1] row_mask:0xf bank_mask:0xf
	s_waitcnt lgkmcnt(0)
	v_add_f32_e32 v8, v8, v9
	s_nop 1
	v_mov_b32_dpp v9, v8 row_shl:4 row_mask:0xf bank_mask:0x5
	v_mov_b32_dpp v9, v8 row_shr:4 row_mask:0xf bank_mask:0xa
	s_waitcnt lgkmcnt(0)
	v_add_f32_e32 v8, v8, v9
	v_fmamk_f32 v8, v8, 0x3c800000, v231
	v_rsq_f32_e32 v8, v8
	s_nop 0
	v_pk_mul_f32 v[12:13], v[12:13], v[8:9] op_sel_hi:[1,0]
	v_pk_mul_f32 v[4:5], v[4:5], v[8:9] op_sel_hi:[1,0]
	v_pk_mul_f32 v[10:11], v[12:13], v[10:11]
	v_pk_mul_f32 v[2:3], v[4:5], v[2:3]
	v_pk_mul_f32 v[4:5], v[28:29], v[8:9] op_sel_hi:[1,0]
	v_pk_mul_f32 v[12:13], v[26:27], v[8:9] op_sel_hi:[1,0]
	v_pk_mul_f32 v[4:5], v[4:5], v[6:7]
	s_waitcnt vmcnt(14)
	v_pk_mul_f32 v[6:7], v[22:23], v[10:11] op_sel:[0,1] op_sel_hi:[1,0]
	v_pk_mul_f32 v[12:13], v[12:13], v[14:15]
	v_sub_f32_e32 v6, v6, v7
	v_mul_f32_e32 v8, v67, v6
	v_pk_mul_f32 v[6:7], v[22:23], v[10:11]
	s_waitcnt vmcnt(12)
	v_and_b32_e32 v14, 0xffff0000, v96
	v_add_f32_e32 v6, v6, v7
	v_mul_f32_e32 v9, v67, v6
	v_pk_mul_f32 v[6:7], v[24:25], v[12:13] op_sel:[0,1] op_sel_hi:[1,0]
	v_and_b32_e32 v15, 0xffff0000, v94
	v_sub_f32_e32 v6, v6, v7
	v_mul_f32_e32 v10, v67, v6
	v_pk_mul_f32 v[6:7], v[24:25], v[12:13]
	v_mov_b32_e32 v17, v15
	v_add_f32_e32 v6, v6, v7
	v_mul_f32_e32 v11, v67, v6
	v_pk_mul_f32 v[6:7], v[18:19], v[2:3] op_sel:[0,1] op_sel_hi:[1,0]
	v_pk_mul_f32 v[2:3], v[18:19], v[2:3]
	v_sub_f32_e32 v6, v6, v7
	v_add_f32_e32 v2, v2, v3
	v_mul_f32_e32 v7, v67, v2
	v_pk_mul_f32 v[2:3], v[20:21], v[4:5] op_sel:[0,1] op_sel_hi:[1,0]
	v_mul_f32_e32 v6, v67, v6
	v_sub_f32_e32 v2, v2, v3
	v_mul_f32_e32 v12, v67, v2
	v_pk_mul_f32 v[2:3], v[20:21], v[4:5]
	v_mov_b32_e32 v19, v14
	v_add_f32_e32 v2, v2, v3
	v_mul_f32_e32 v5, v67, v2
	v_cvt_pk_bf16_f32 v2, v8, v10
	v_cvt_pk_bf16_f32 v3, v6, v12
	v_cvt_pk_bf16_f32 v4, v9, v11
	v_cvt_pk_bf16_f32 v5, v7, v5
	v_lshl_add_u64 v[6:7], v[84:85], 0, v[72:73]
	global_store_dwordx2 v[6:7], v[2:3], off
	global_store_dwordx2 v[6:7], v[4:5], off offset:64
	v_and_b32_e32 v2, 4, v90
	v_cmp_ne_u32_e32 vcc, 0, v2
	v_lshlrev_b32_e32 v2, 16, v97
	v_and_b32_e32 v6, 0xffff0000, v97
	v_lshlrev_b32_e32 v3, 16, v95
	v_and_b32_e32 v7, 0xffff0000, v95
	v_mov_b32_e32 v10, v6
	v_mov_b32_e32 v11, v2
	v_mov_b32_e32 v8, v7
	v_mov_b32_e32 v9, v3
	v_pk_mul_f32 v[10:11], v[10:11], v[10:11]
	s_waitcnt vmcnt(12)
	v_mov_b32_e32 v4, v48
	v_pk_fma_f32 v[8:9], v[8:9], v[8:9], v[10:11]
	v_lshlrev_b32_e32 v10, 16, v96
	v_lshlrev_b32_e32 v11, 16, v94
	v_mov_b32_e32 v18, v10
	v_mov_b32_e32 v16, v11
	v_pk_mul_f32 v[18:19], v[18:19], v[18:19]
	v_mov_b32_e32 v5, v44
	v_pk_fma_f32 v[16:17], v[16:17], v[16:17], v[18:19]
	v_mov_b32_e32 v12, v46
	v_add_f32_e32 v16, v16, v17
	v_add_f32_e32 v9, v9, v16
	v_add_f32_e32 v8, v8, v9
	s_nop 1
	v_mov_b32_dpp v9, v8 quad_perm:[1,0,3,2] row_mask:0xf bank_mask:0xf
	v_mov_b32_e32 v13, v42
	v_mov_b32_e32 v44, v49
	v_cndmask_b32_e64 v20, v237, 1.0, vcc
	v_mov_b32_e32 v42, v47
	s_waitcnt lgkmcnt(0)
	v_add_f32_e32 v8, v8, v9
	s_nop 1
	v_mov_b32_dpp v9, v8 quad_perm:[2,3,0,1] row_mask:0xf bank_mask:0xf
	s_waitcnt lgkmcnt(0)
	v_add_f32_e32 v8, v8, v9
	s_nop 1
	v_mov_b32_dpp v9, v8 row_shl:4 row_mask:0xf bank_mask:0x5
	v_mov_b32_dpp v9, v8 row_shr:4 row_mask:0xf bank_mask:0xa
	s_waitcnt lgkmcnt(0)
	v_add_f32_e32 v8, v8, v9
	v_fmamk_f32 v8, v8, 0x3c800000, v231
	v_rsq_f32_e32 v8, v8
	s_nop 0
	v_pk_mul_f32 v[12:13], v[12:13], v[8:9] op_sel_hi:[1,0]
	v_pk_mul_f32 v[4:5], v[4:5], v[8:9] op_sel_hi:[1,0]
	v_pk_mul_f32 v[10:11], v[12:13], v[10:11]
	v_pk_mul_f32 v[2:3], v[4:5], v[2:3]
	v_pk_mul_f32 v[4:5], v[44:45], v[8:9] op_sel_hi:[1,0]
	v_pk_mul_f32 v[12:13], v[42:43], v[8:9] op_sel_hi:[1,0]
	v_pk_mul_f32 v[4:5], v[4:5], v[6:7]
	s_waitcnt vmcnt(10)
; __device__ __forceinline__ unsigned cvt_pk_bf16(float lo, float hi) { unsigned r; asm volatile("v_cvt_pk_bf16_f32 %0, %1, %2" : "=v"(r) : "v"(lo), "v"(hi)); return r; }
; __device__ __forceinline__ float bf2f(unsigned h) { return __uint_as_float(h << 16); }
; template <int D> __device__ __forceinline__ void hv_finish(const HVRaw& r, bool norm, bool rope, float scale, bf16_t* __restrict__ dst, const int sub) {
;     constexpr int NH = D / 16;
;     float lo[4], hi[4], cc[4], sn[4];
;     lo[0] = bf2f(r.a.x & 0xffffu); lo[1] = bf2f(r.a.x >> 16); lo[2] = bf2f(r.a.y & 0xffffu); lo[3] = bf2f(r.a.y >> 16);
;     hi[0] = bf2f(r.b.x & 0xffffu); hi[1] = bf2f(r.b.x >> 16); hi[2] = bf2f(r.b.y & 0xffffu); hi[3] = bf2f(r.b.y >> 16);
;     float ss = 0.f;
; #pragma unroll
;     for (int i = 0; i < NH; ++i) ss += lo[i] * lo[i] + hi[i] * hi[i];
;     ss += __shfl_xor(ss, 1); ss += __shfl_xor(ss, 2); ss += __shfl_xor(ss, 4);
;     const float rs = norm ? __builtin_amdgcn_rsqf(ss * (1.0f / D) + EPS) : 1.0f;
; #pragma unroll
;     for (int i = 0; i < NH; ++i) { lo[i] *= norm ? rs * r.g0[i] : 1.0f; hi[i] *= norm ? rs * r.g1[i] : 1.0f; }
;     cc[0] = r.c0[0]; sn[0] = r.c0[1]; cc[1] = r.c0[2]; sn[1] = r.c0[3]; cc[2] = r.c1[0]; sn[2] = r.c1[1]; cc[3] = r.c1[2]; sn[3] = r.c1[3];
;     float ol[4], oh[4];
; #pragma unroll
;     for (int i = 0; i < NH; ++i) {
;         const float c = rope ? cc[i] : 1.0f, sv = rope ? sn[i] : 0.0f;
;         ol[i] = (lo[i] * c - hi[i] * sv) * scale; oh[i] = (hi[i] * c + lo[i] * sv) * scale;
;     }
;     if (NH == 4) {
;         u32x2 w0, w1; w0.x = pg8::cvt_pk_bf16(ol[0], ol[1]); w0.y = pg8::cvt_pk_bf16(ol[2], ol[3]); w1.x = pg8::cvt_pk_bf16(oh[0], oh[1]); w1.y = pg8::cvt_pk_bf16(oh[2], oh[3]);
;         *(u32x2*)(dst + sub * 4) = w0; *(u32x2*)(dst + 32 + sub * 4) = w1;
;     } else {
;         *(unsigned*)(dst + sub * 2) = pg8::cvt_pk_bf16(ol[0], ol[1]); *(unsigned*)(dst + 16 + sub * 2) = pg8::cvt_pk_bf16(oh[0], oh[1]);
;     }
; }
; __global__ void __launch_bounds__(512, 2) mega_fwd(KArgs a) {
;     ...
; #pragma unroll
;                 for (int u4 = 0; u4 < 4; ++u4) hv_finish<64>(hr[u4], true, true, isk[u4] ? 1.0f : 0.125f * LOG2E, dsts[u4], lane & 7);
;             }
	v_pk_mul_f32 v[6:7], v[38:39], v[10:11] op_sel:[0,1] op_sel_hi:[1,0]
	v_pk_mul_f32 v[12:13], v[12:13], v[14:15]
	v_sub_f32_e32 v6, v6, v7
	v_mul_f32_e32 v8, v20, v6
	v_pk_mul_f32 v[6:7], v[38:39], v[10:11]
	s_waitcnt vmcnt(8)
	v_and_b32_e32 v14, 0xffff0000, v104
	v_add_f32_e32 v6, v6, v7
	v_mul_f32_e32 v9, v20, v6
	v_pk_mul_f32 v[6:7], v[40:41], v[12:13] op_sel:[0,1] op_sel_hi:[1,0]
	v_and_b32_e32 v15, 0xffff0000, v102
	v_sub_f32_e32 v6, v6, v7
	v_mul_f32_e32 v10, v20, v6
	v_pk_mul_f32 v[6:7], v[40:41], v[12:13]
	v_mov_b32_e32 v19, v14
	v_add_f32_e32 v6, v6, v7
	v_mul_f32_e32 v11, v20, v6
	v_pk_mul_f32 v[6:7], v[34:35], v[2:3] op_sel:[0,1] op_sel_hi:[1,0]
	v_pk_mul_f32 v[2:3], v[34:35], v[2:3]
	v_sub_f32_e32 v6, v6, v7
	v_add_f32_e32 v2, v2, v3
	v_mul_f32_e32 v7, v20, v2
	v_pk_mul_f32 v[2:3], v[36:37], v[4:5] op_sel:[0,1] op_sel_hi:[1,0]
	v_mul_f32_e32 v6, v20, v6
	v_sub_f32_e32 v2, v2, v3
	v_mul_f32_e32 v12, v20, v2
	v_pk_mul_f32 v[2:3], v[36:37], v[4:5]
	v_mov_b32_e32 v17, v15
	v_add_f32_e32 v2, v2, v3
	v_mul_f32_e32 v5, v20, v2
	v_cvt_pk_bf16_f32 v2, v8, v10
	v_cvt_pk_bf16_f32 v3, v6, v12
	v_cvt_pk_bf16_f32 v4, v9, v11
	v_cvt_pk_bf16_f32 v5, v7, v5
	v_lshl_add_u64 v[6:7], v[92:93], 0, v[72:73]
	global_store_dwordx2 v[6:7], v[2:3], off
	global_store_dwordx2 v[6:7], v[4:5], off offset:64
	v_and_b32_e32 v2, 4, v98
	v_cmp_ne_u32_e32 vcc, 0, v2
	v_lshlrev_b32_e32 v2, 16, v105
	v_and_b32_e32 v6, 0xffff0000, v105
	v_lshlrev_b32_e32 v3, 16, v103
	v_and_b32_e32 v7, 0xffff0000, v103
	v_mov_b32_e32 v10, v6
	v_mov_b32_e32 v11, v2
	v_mov_b32_e32 v8, v7
	v_mov_b32_e32 v9, v3
	v_pk_mul_f32 v[10:11], v[10:11], v[10:11]
	s_waitcnt vmcnt(8)
	v_mov_b32_e32 v4, v64
	v_pk_fma_f32 v[8:9], v[8:9], v[8:9], v[10:11]
	v_lshlrev_b32_e32 v10, 16, v104
	v_lshlrev_b32_e32 v11, 16, v102
	v_mov_b32_e32 v18, v10
	v_mov_b32_e32 v16, v11
	v_pk_mul_f32 v[18:19], v[18:19], v[18:19]
	v_mov_b32_e32 v5, v60
	v_pk_fma_f32 v[16:17], v[16:17], v[16:17], v[18:19]
	v_mov_b32_e32 v12, v62
	v_add_f32_e32 v16, v16, v17
	v_add_f32_e32 v9, v9, v16
	v_add_f32_e32 v8, v8, v9
	s_nop 1
	v_mov_b32_dpp v9, v8 quad_perm:[1,0,3,2] row_mask:0xf bank_mask:0xf
	v_mov_b32_e32 v13, v58
	v_mov_b32_e32 v60, v65
	v_cndmask_b32_e64 v20, v237, 1.0, vcc
	v_mov_b32_e32 v58, v63
	s_waitcnt lgkmcnt(0)
	v_add_f32_e32 v8, v8, v9
	s_nop 1
	v_mov_b32_dpp v9, v8 quad_perm:[2,3,0,1] row_mask:0xf bank_mask:0xf
	v_cmp_lt_i32_e32 vcc, s16, v1
	v_add_u32_e32 v1, 0x80000, v1
	s_or_b64 s[12:13], vcc, s[12:13]
	s_waitcnt lgkmcnt(0)
	v_add_f32_e32 v8, v8, v9
	s_nop 1
	v_mov_b32_dpp v9, v8 row_shl:4 row_mask:0xf bank_mask:0x5
	v_mov_b32_dpp v9, v8 row_shr:4 row_mask:0xf bank_mask:0xa
	s_waitcnt lgkmcnt(0)
	v_add_f32_e32 v8, v8, v9
	v_fmamk_f32 v8, v8, 0x3c800000, v231
	v_rsq_f32_e32 v8, v8
	s_nop 0
	v_pk_mul_f32 v[12:13], v[12:13], v[8:9] op_sel_hi:[1,0]
	v_pk_mul_f32 v[4:5], v[4:5], v[8:9] op_sel_hi:[1,0]
	v_pk_mul_f32 v[10:11], v[12:13], v[10:11]
	v_pk_mul_f32 v[2:3], v[4:5], v[2:3]
	v_pk_mul_f32 v[4:5], v[60:61], v[8:9] op_sel_hi:[1,0]
	v_pk_mul_f32 v[12:13], v[58:59], v[8:9] op_sel_hi:[1,0]
	v_pk_mul_f32 v[4:5], v[4:5], v[6:7]
	s_waitcnt vmcnt(6)
	v_pk_mul_f32 v[6:7], v[54:55], v[10:11] op_sel:[0,1] op_sel_hi:[1,0]
	v_pk_mul_f32 v[12:13], v[12:13], v[14:15]
	v_sub_f32_e32 v6, v6, v7
	v_mul_f32_e32 v8, v20, v6
	v_pk_mul_f32 v[6:7], v[54:55], v[10:11]
	s_nop 0
	v_add_f32_e32 v6, v6, v7
	v_mul_f32_e32 v9, v20, v6
	v_pk_mul_f32 v[6:7], v[56:57], v[12:13] op_sel:[0,1] op_sel_hi:[1,0]
	s_nop 0
	v_sub_f32_e32 v6, v6, v7
	v_mul_f32_e32 v10, v20, v6
	v_pk_mul_f32 v[6:7], v[56:57], v[12:13]
	s_nop 0
	v_add_f32_e32 v6, v6, v7
	v_mul_f32_e32 v11, v20, v6
	v_pk_mul_f32 v[6:7], v[50:51], v[2:3] op_sel:[0,1] op_sel_hi:[1,0]
	v_pk_mul_f32 v[2:3], v[50:51], v[2:3]
	v_sub_f32_e32 v6, v6, v7
	v_add_f32_e32 v2, v2, v3
	v_mul_f32_e32 v7, v20, v2
	v_pk_mul_f32 v[2:3], v[52:53], v[4:5] op_sel:[0,1] op_sel_hi:[1,0]
	v_mul_f32_e32 v6, v20, v6
	v_sub_f32_e32 v2, v2, v3
	v_mul_f32_e32 v12, v20, v2
	v_pk_mul_f32 v[2:3], v[52:53], v[4:5]
	s_nop 0
	v_add_f32_e32 v2, v2, v3
	v_mul_f32_e32 v5, v20, v2
	v_cvt_pk_bf16_f32 v2, v8, v10
	v_cvt_pk_bf16_f32 v3, v6, v12
	v_cvt_pk_bf16_f32 v4, v9, v11
	v_cvt_pk_bf16_f32 v5, v7, v5
	v_lshl_add_u64 v[6:7], v[100:101], 0, v[72:73]
	global_store_dwordx2 v[6:7], v[2:3], off
	global_store_dwordx2 v[6:7], v[4:5], off offset:64
	s_andn2_b64 exec, exec, s[12:13]
	s_cbranch_execnz .LBB0_4077

; template <int D> __device__ __forceinline__ void hv_load(HVRaw& r, const bf16_t* __restrict__ src, const float* __restrict__ gain, const f32x2* __restrict__ cs, const int sub) {
;     if (D == 64) {
;         r.a = *(const u32x2*)(src + sub * 4); r.b = *(const u32x2*)(src + 32 + sub * 4);
;         r.g0 = *(const f32x4*)(gain + sub * 4); r.g1 = *(const f32x4*)(gain + 32 + sub * 4);
;         r.c0 = *(const f32x4*)(cs + sub * 4); r.c1 = *(const f32x4*)(cs + sub * 4 + 2);
;     } else {
;         r.a.x = *(const unsigned*)(src + sub * 2); r.b.x = *(const unsigned*)(src + 16 + sub * 2); r.a.y = 0u; r.b.y = 0u;
;         const f32x2 g0 = *(const f32x2*)(gain + sub * 2), g1 = *(const f32x2*)(gain + 16 + sub * 2);
;         r.g0 = (f32x4){g0.x, g0.y, 0.f, 0.f}; r.g1 = (f32x4){g1.x, g1.y, 0.f, 0.f};
;         r.c0 = *(const f32x4*)(cs + sub * 2); r.c1 = r.c0;
;     }
; }
; template <int D> __device__ __forceinline__ void hv_finish(const HVRaw& r, bool norm, bool rope, float scale, bf16_t* __restrict__ dst, const int sub) {
;     constexpr int NH = D / 16;
;     float lo[4], hi[4], cc[4], sn[4];
;     lo[0] = bf2f(r.a.x & 0xffffu); lo[1] = bf2f(r.a.x >> 16); lo[2] = bf2f(r.a.y & 0xffffu); lo[3] = bf2f(r.a.y >> 16);
;     hi[0] = bf2f(r.b.x & 0xffffu); hi[1] = bf2f(r.b.x >> 16); hi[2] = bf2f(r.b.y & 0xffffu); hi[3] = bf2f(r.b.y >> 16);
;     float ss = 0.f;
; #pragma unroll
;     for (int i = 0; i < NH; ++i) ss += lo[i] * lo[i] + hi[i] * hi[i];
;     ss += __shfl_xor(ss, 1); ss += __shfl_xor(ss, 2); ss += __shfl_xor(ss, 4);
; __global__ void __launch_bounds__(512, 2) mega_fwd(KArgs a) {
;     ...
;             for (int e0 = gw * 64 + lane; e0 < T_ * 16 * 8; e0 += NGW * 64 * 4) {
;                 HVRaw hr[4]; bf16_t* dsts[4]; bool isk[4];
; #pragma unroll
;                 for (int u4 = 0; u4 < 4; ++u4) {
;                     const int ev = (e0 + u4 * NGW * 64) >> 3, t = ev >> 4, which = (ev >> 3) & 1, h = ev & 7;
;                     dsts[u4] = (which ? KM : QM) + ((size_t)t * 8 + h) * 96; isk[u4] = which != 0;
;                     hv_load<64>(hr[u4], RA + (size_t)t * 1792 + (which ? 768 + h * 128 : h * 96), which ? mkg : mqg, CS64, lane & 7);
;                 }
; #pragma unroll
;                 for (int u4 = 0; u4 < 4; ++u4) hv_finish<64>(hr[u4], true, false, isk[u4] ? 1.0f : SCQ, dsts[u4], lane & 7);
.LBB0_4225:
	v_and_b32_e32 v2, 64, v9
	v_bfe_u32 v40, v9, 3, 3
	v_cmp_eq_u32_e32 vcc, 0, v2
	v_mov_b32_e32 v2, 0x300
	v_lshl_add_u32 v4, v40, 7, v2
	v_mul_u32_u24_e32 v5, 0x60, v40
	v_mov_b32_e32 v2, 0x14400000
	v_mov_b32_e32 v3, 0x12c00000
	v_cndmask_b32_e32 v11, v4, v5, vcc
	v_mov_b32_e32 v4, s16
	v_mov_b32_e32 v5, s3
	v_ashrrev_i32_e32 v10, 7, v9
	v_cndmask_b32_e32 v2, v2, v3, vcc
	v_mov_b32_e32 v3, v0
	v_cndmask_b32_e32 v5, v4, v5, vcc
	v_mov_b32_e32 v4, s15
	v_mov_b32_e32 v12, s2
	v_cndmask_b32_e32 v4, v4, v12, vcc
	v_lshl_add_u64 v[12:13], s[6:7], 0, v[2:3]
	v_lshl_or_b32 v2, v10, 3, v40
	v_mov_b64_e32 v[20:21], s[8:9]
	v_mad_i64_i32 v[18:19], s[18:19], v2, s27, v[12:13]
	v_mad_i64_i32 v[2:3], s[18:19], v10, s74, v[20:21]
	v_lshlrev_b32_e32 v22, 1, v11
	v_mov_b32_e32 v23, v0
	v_lshl_add_u64 v[2:3], v[2:3], 0, v[22:23]
	v_lshlrev_b32_e32 v10, 1, v8
	v_mov_b32_e32 v11, v0
	v_lshl_add_u64 v[2:3], v[2:3], 0, v[10:11]
	global_load_dwordx2 v[24:25], v[2:3], off
	global_load_dwordx2 v[26:27], v[2:3], off offset:64
	v_lshlrev_b32_e32 v2, 2, v8
	v_mov_b32_e32 v3, v0
	v_lshl_add_u64 v[14:15], v[4:5], 0, v[2:3]
	global_load_dwordx4 v[2:5], v[14:15], off
	s_nop 0
	global_load_dwordx4 v[14:17], v[14:15], off offset:128
	v_add_u32_e32 v28, 0x20000, v9
	v_ashrrev_i32_e32 v30, 7, v28
	v_lshl_or_b32 v28, v30, 3, v40
	v_mad_i64_i32 v[30:31], s[18:19], v30, s74, v[20:21]
	v_lshl_add_u64 v[30:31], v[30:31], 0, v[22:23]
	v_lshl_add_u64 v[30:31], v[30:31], 0, v[10:11]
	global_load_dwordx2 v[32:33], v[30:31], off
	s_nop 0
	global_load_dwordx2 v[30:31], v[30:31], off offset:64
	v_add_u32_e32 v34, 0x40000, v9
	v_add_u32_e32 v41, 0x60000, v9
	v_ashrrev_i32_e32 v36, 7, v34
	v_ashrrev_i32_e32 v41, 7, v41
	v_lshl_or_b32 v34, v36, 3, v40
	v_mad_i64_i32 v[36:37], s[18:19], v36, s74, v[20:21]
	v_lshl_or_b32 v40, v41, 3, v40
	v_mad_i64_i32 v[28:29], s[18:19], v28, s27, v[12:13]
	v_mad_i64_i32 v[34:35], s[18:19], v34, s27, v[12:13]
	v_lshl_add_u64 v[36:37], v[36:37], 0, v[22:23]
	v_mad_i64_i32 v[12:13], s[18:19], v40, s27, v[12:13]
	v_mov_b32_e32 v40, 0x3e16c740
	v_lshl_add_u64 v[36:37], v[36:37], 0, v[10:11]
	v_cndmask_b32_e32 v54, 1.0, v40, vcc
	global_load_dwordx2 v[38:39], v[36:37], off
	s_nop 0
	global_load_dwordx2 v[36:37], v[36:37], off offset:64
	v_mad_i64_i32 v[20:21], s[18:19], v41, s74, v[20:21]
	v_lshl_add_u64 v[20:21], v[20:21], 0, v[22:23]
	v_lshl_add_u64 v[20:21], v[20:21], 0, v[10:11]
	global_load_dwordx2 v[22:23], v[20:21], off
	s_nop 0
	global_load_dwordx2 v[20:21], v[20:21], off offset:64
	v_lshl_add_u64 v[18:19], v[18:19], 0, v[10:11]
	s_mov_b32 s17, 0x17ffff
	v_cmp_lt_i32_e32 vcc, s17, v9
	v_add_u32_e32 v9, 0x80000, v9
	s_or_b64 s[10:11], vcc, s[10:11]
	s_waitcnt vmcnt(9)
	v_lshlrev_b32_e32 v41, 16, v25
	s_waitcnt vmcnt(8)
	v_lshlrev_b32_e32 v40, 16, v27
	v_and_b32_e32 v44, 0xffff0000, v27
	v_and_b32_e32 v45, 0xffff0000, v25
	v_mov_b32_e32 v48, v44
	v_mov_b32_e32 v49, v40
	v_mov_b32_e32 v46, v45
	v_mov_b32_e32 v47, v41
	v_pk_mul_f32 v[48:49], v[48:49], v[48:49]
	v_and_b32_e32 v25, 0xffff0000, v24
	v_pk_fma_f32 v[46:47], v[46:47], v[46:47], v[48:49]
	v_lshlrev_b32_e32 v49, 16, v24
	v_lshlrev_b32_e32 v48, 16, v26
	v_and_b32_e32 v24, 0xffff0000, v26
	v_mov_b32_e32 v52, v48
	v_mov_b32_e32 v53, v24
	v_mov_b32_e32 v26, v49
	v_mov_b32_e32 v27, v25
	v_pk_mul_f32 v[52:53], v[52:53], v[52:53]
	s_waitcnt vmcnt(7)
	v_mov_b32_e32 v51, v2
	v_pk_fma_f32 v[26:27], v[26:27], v[26:27], v[52:53]
	v_mov_b32_e32 v43, v4
	v_add_f32_e32 v2, v26, v27
	v_add_f32_e32 v2, v47, v2
	v_add_f32_e32 v2, v46, v2
	s_nop 1
	v_mov_b32_dpp v4, v2 quad_perm:[1,0,3,2] row_mask:0xf bank_mask:0xf
	s_waitcnt vmcnt(6)
	v_mov_b32_e32 v50, v14
	v_mov_b32_e32 v42, v16
	s_waitcnt lgkmcnt(0)
	v_add_f32_e32 v2, v2, v4
	s_nop 1
	v_mov_b32_dpp v4, v2 quad_perm:[2,3,0,1] row_mask:0xf bank_mask:0xf
	s_waitcnt lgkmcnt(0)
	v_add_f32_e32 v2, v2, v4
	s_nop 1
	v_mov_b32_dpp v4, v2 row_shl:4 row_mask:0xf bank_mask:0x5
	v_mov_b32_dpp v4, v2 row_shr:4 row_mask:0xf bank_mask:0xa
	s_waitcnt lgkmcnt(0)
	v_add_f32_e32 v2, v2, v4
	v_fmamk_f32 v2, v2, 0x3c800000, v231
	v_rsq_f32_e32 v14, v2
	v_mov_b32_e32 v2, v15
	v_mov_b32_e32 v4, v17
	v_pk_mul_f32 v[26:27], v[50:51], v[14:15] op_sel_hi:[1,0]
	v_pk_mul_f32 v[46:47], v[2:3], v[14:15] op_sel_hi:[1,0]
	v_pk_mul_f32 v[26:27], v[26:27], v[48:49]
	v_pk_mul_f32 v[24:25], v[46:47], v[24:25]
	v_pk_mul_f32 v[46:47], v[42:43], v[14:15] op_sel_hi:[1,0]
	v_pk_mul_f32 v[14:15], v[4:5], v[14:15] op_sel_hi:[1,0]
	v_pk_mul_f32 v[40:41], v[46:47], v[40:41]
	v_fmamk_f32 v16, v26, 0x80000000, v27
	v_fmac_f32_e32 v26, 0, v27
	v_pk_mul_f32 v[14:15], v[14:15], v[44:45]
	v_mul_f32_e32 v17, v54, v26
	v_fmamk_f32 v26, v24, 0x80000000, v25
	v_fmac_f32_e32 v24, 0, v25
	v_fmamk_f32 v25, v40, 0x80000000, v41
	v_fmac_f32_e32 v40, 0, v41
	v_mul_f32_e32 v16, v54, v16
	v_mul_f32_e32 v27, v54, v40
	v_fmamk_f32 v40, v14, 0x80000000, v15
	v_fmac_f32_e32 v14, 0, v15
	v_mul_f32_e32 v26, v54, v26
	v_mul_f32_e32 v24, v54, v24
	v_mul_f32_e32 v25, v54, v25
	v_mul_f32_e32 v40, v54, v40
	v_mul_f32_e32 v41, v54, v14
	v_cvt_pk_bf16_f32 v14, v16, v26
	v_cvt_pk_bf16_f32 v15, v25, v40
	v_cvt_pk_bf16_f32 v16, v17, v24
	v_cvt_pk_bf16_f32 v17, v27, v41
	global_store_dwordx2 v[18:19], v[14:15], off
	global_store_dwordx2 v[18:19], v[16:17], off offset:64
	s_waitcnt vmcnt(6)
; __device__ __forceinline__ unsigned cvt_pk_bf16(float lo, float hi) { unsigned r; asm volatile("v_cvt_pk_bf16_f32 %0, %1, %2" : "=v"(r) : "v"(lo), "v"(hi)); return r; }
; __device__ __forceinline__ float bf2f(unsigned h) { return __uint_as_float(h << 16); }
; template <int D> __device__ __forceinline__ void hv_finish(const HVRaw& r, bool norm, bool rope, float scale, bf16_t* __restrict__ dst, const int sub) {
;     constexpr int NH = D / 16;
;     float lo[4], hi[4], cc[4], sn[4];
;     lo[0] = bf2f(r.a.x & 0xffffu); lo[1] = bf2f(r.a.x >> 16); lo[2] = bf2f(r.a.y & 0xffffu); lo[3] = bf2f(r.a.y >> 16);
;     hi[0] = bf2f(r.b.x & 0xffffu); hi[1] = bf2f(r.b.x >> 16); hi[2] = bf2f(r.b.y & 0xffffu); hi[3] = bf2f(r.b.y >> 16);
;     float ss = 0.f;
; #pragma unroll
;     for (int i = 0; i < NH; ++i) ss += lo[i] * lo[i] + hi[i] * hi[i];
;     ss += __shfl_xor(ss, 1); ss += __shfl_xor(ss, 2); ss += __shfl_xor(ss, 4);
;     const float rs = norm ? __builtin_amdgcn_rsqf(ss * (1.0f / D) + EPS) : 1.0f;
; #pragma unroll
;     for (int i = 0; i < NH; ++i) { lo[i] *= norm ? rs * r.g0[i] : 1.0f; hi[i] *= norm ? rs * r.g1[i] : 1.0f; }
;     cc[0] = r.c0[0]; sn[0] = r.c0[1]; cc[1] = r.c0[2]; sn[1] = r.c0[3]; cc[2] = r.c1[0]; sn[2] = r.c1[1]; cc[3] = r.c1[2]; sn[3] = r.c1[3];
;     float ol[4], oh[4];
; #pragma unroll
;     for (int i = 0; i < NH; ++i) {
;         const float c = rope ? cc[i] : 1.0f, sv = rope ? sn[i] : 0.0f;
;         ol[i] = (lo[i] * c - hi[i] * sv) * scale; oh[i] = (hi[i] * c + lo[i] * sv) * scale;
;     }
;     if (NH == 4) {
;         u32x2 w0, w1; w0.x = pg8::cvt_pk_bf16(ol[0], ol[1]); w0.y = pg8::cvt_pk_bf16(ol[2], ol[3]); w1.x = pg8::cvt_pk_bf16(oh[0], oh[1]); w1.y = pg8::cvt_pk_bf16(oh[2], oh[3]);
;         *(u32x2*)(dst + sub * 4) = w0; *(u32x2*)(dst + 32 + sub * 4) = w1;
;     } else {
;         *(unsigned*)(dst + sub * 2) = pg8::cvt_pk_bf16(ol[0], ol[1]); *(unsigned*)(dst + 16 + sub * 2) = pg8::cvt_pk_bf16(oh[0], oh[1]);
;     }
; }
	v_lshlrev_b32_e32 v14, 16, v31
	v_and_b32_e32 v16, 0xffff0000, v31
	v_lshlrev_b32_e32 v15, 16, v33
	v_and_b32_e32 v17, 0xffff0000, v33
	v_mov_b32_e32 v24, v16
	v_mov_b32_e32 v25, v14
	v_mov_b32_e32 v18, v17
	v_mov_b32_e32 v19, v15
	v_pk_mul_f32 v[24:25], v[24:25], v[24:25]
	v_and_b32_e32 v26, 0xffff0000, v30
	v_pk_fma_f32 v[18:19], v[18:19], v[18:19], v[24:25]
	v_lshlrev_b32_e32 v24, 16, v30
	v_lshlrev_b32_e32 v25, 16, v32
	v_and_b32_e32 v27, 0xffff0000, v32
	v_mov_b32_e32 v32, v24
	v_mov_b32_e32 v33, v26
	v_mov_b32_e32 v30, v25
	v_mov_b32_e32 v31, v27
	v_pk_mul_f32 v[32:33], v[32:33], v[32:33]
	s_nop 0
	v_pk_fma_f32 v[30:31], v[30:31], v[30:31], v[32:33]
	s_nop 0
	v_add_f32_e32 v30, v30, v31
	v_add_f32_e32 v19, v19, v30
	v_add_f32_e32 v18, v18, v19
	s_nop 1
	v_mov_b32_dpp v19, v18 quad_perm:[1,0,3,2] row_mask:0xf bank_mask:0xf
	s_waitcnt lgkmcnt(0)
	v_add_f32_e32 v18, v18, v19
	s_nop 1
	v_mov_b32_dpp v19, v18 quad_perm:[2,3,0,1] row_mask:0xf bank_mask:0xf
	s_waitcnt lgkmcnt(0)
	v_add_f32_e32 v18, v18, v19
	s_nop 1
	v_mov_b32_dpp v19, v18 row_shl:4 row_mask:0xf bank_mask:0x5
	v_mov_b32_dpp v19, v18 row_shr:4 row_mask:0xf bank_mask:0xa
	s_waitcnt lgkmcnt(0)
	v_add_f32_e32 v18, v18, v19
	v_fmamk_f32 v18, v18, 0x3c800000, v231
	v_rsq_f32_e32 v18, v18
	s_nop 0
	v_pk_mul_f32 v[30:31], v[50:51], v[18:19] op_sel_hi:[1,0]
	s_nop 0
	v_pk_mul_f32 v[24:25], v[30:31], v[24:25]
	v_pk_mul_f32 v[30:31], v[2:3], v[18:19] op_sel_hi:[1,0]
	s_nop 0
	v_pk_mul_f32 v[26:27], v[30:31], v[26:27]
	v_pk_mul_f32 v[30:31], v[42:43], v[18:19] op_sel_hi:[1,0]
	v_pk_mul_f32 v[18:19], v[4:5], v[18:19] op_sel_hi:[1,0]
	v_pk_mul_f32 v[14:15], v[30:31], v[14:15]
	v_pk_mul_f32 v[16:17], v[18:19], v[16:17]
	v_fmamk_f32 v18, v24, 0x80000000, v25
	v_fmac_f32_e32 v24, 0, v25
	v_mul_f32_e32 v19, v54, v24
	v_fmamk_f32 v24, v26, 0x80000000, v27
	v_fmac_f32_e32 v26, 0, v27
	v_mul_f32_e32 v25, v54, v26
	v_fmamk_f32 v26, v14, 0x80000000, v15
	v_fmac_f32_e32 v14, 0, v15
	v_mul_f32_e32 v27, v54, v14
	v_fmamk_f32 v14, v16, 0x80000000, v17
	v_mul_f32_e32 v18, v54, v18
	v_mul_f32_e32 v15, v54, v14
	v_fmac_f32_e32 v16, 0, v17
	v_mul_f32_e32 v24, v54, v24
	v_mul_f32_e32 v26, v54, v26
	v_mul_f32_e32 v17, v54, v16
	v_cvt_pk_bf16_f32 v14, v18, v24
	v_cvt_pk_bf16_f32 v15, v26, v15
	v_cvt_pk_bf16_f32 v16, v19, v25
	v_lshl_add_u64 v[18:19], v[28:29], 0, v[10:11]
	v_cvt_pk_bf16_f32 v17, v27, v17
	global_store_dwordx2 v[18:19], v[14:15], off
	global_store_dwordx2 v[18:19], v[16:17], off offset:64
	s_waitcnt vmcnt(6)
	v_lshlrev_b32_e32 v14, 16, v37
	v_and_b32_e32 v16, 0xffff0000, v37
	v_lshlrev_b32_e32 v15, 16, v39
	v_and_b32_e32 v17, 0xffff0000, v39
	v_mov_b32_e32 v24, v16
	v_mov_b32_e32 v25, v14
	v_mov_b32_e32 v18, v17
	v_mov_b32_e32 v19, v15
	v_pk_mul_f32 v[24:25], v[24:25], v[24:25]
	v_and_b32_e32 v26, 0xffff0000, v36
	v_pk_fma_f32 v[18:19], v[18:19], v[18:19], v[24:25]
	v_lshlrev_b32_e32 v24, 16, v36
	v_lshlrev_b32_e32 v25, 16, v38
	v_and_b32_e32 v27, 0xffff0000, v38
	v_mov_b32_e32 v30, v24
	v_mov_b32_e32 v31, v26
	v_mov_b32_e32 v28, v25
	v_mov_b32_e32 v29, v27
	v_pk_mul_f32 v[30:31], v[30:31], v[30:31]
	s_nop 0
	v_pk_fma_f32 v[28:29], v[28:29], v[28:29], v[30:31]
	s_nop 0
	v_add_f32_e32 v28, v28, v29
	v_add_f32_e32 v19, v19, v28
	v_add_f32_e32 v18, v18, v19
	s_nop 1
	v_mov_b32_dpp v19, v18 quad_perm:[1,0,3,2] row_mask:0xf bank_mask:0xf
	s_waitcnt lgkmcnt(0)
	v_add_f32_e32 v18, v18, v19
	s_nop 1
	v_mov_b32_dpp v19, v18 quad_perm:[2,3,0,1] row_mask:0xf bank_mask:0xf
	s_waitcnt lgkmcnt(0)
	v_add_f32_e32 v18, v18, v19
	s_nop 1
	v_mov_b32_dpp v19, v18 row_shl:4 row_mask:0xf bank_mask:0x5
	v_mov_b32_dpp v19, v18 row_shr:4 row_mask:0xf bank_mask:0xa
	s_waitcnt lgkmcnt(0)
; __device__ __forceinline__ unsigned cvt_pk_bf16(float lo, float hi) { unsigned r; asm volatile("v_cvt_pk_bf16_f32 %0, %1, %2" : "=v"(r) : "v"(lo), "v"(hi)); return r; }
; __device__ __forceinline__ float bf2f(unsigned h) { return __uint_as_float(h << 16); }
; template <int D> __device__ __forceinline__ void hv_finish(const HVRaw& r, bool norm, bool rope, float scale, bf16_t* __restrict__ dst, const int sub) {
;     constexpr int NH = D / 16;
;     float lo[4], hi[4], cc[4], sn[4];
;     lo[0] = bf2f(r.a.x & 0xffffu); lo[1] = bf2f(r.a.x >> 16); lo[2] = bf2f(r.a.y & 0xffffu); lo[3] = bf2f(r.a.y >> 16);
;     hi[0] = bf2f(r.b.x & 0xffffu); hi[1] = bf2f(r.b.x >> 16); hi[2] = bf2f(r.b.y & 0xffffu); hi[3] = bf2f(r.b.y >> 16);
;     float ss = 0.f;
; #pragma unroll
;     for (int i = 0; i < NH; ++i) ss += lo[i] * lo[i] + hi[i] * hi[i];
;     ss += __shfl_xor(ss, 1); ss += __shfl_xor(ss, 2); ss += __shfl_xor(ss, 4);
;     const float rs = norm ? __builtin_amdgcn_rsqf(ss * (1.0f / D) + EPS) : 1.0f;
; #pragma unroll
;     for (int i = 0; i < NH; ++i) { lo[i] *= norm ? rs * r.g0[i] : 1.0f; hi[i] *= norm ? rs * r.g1[i] : 1.0f; }
;     cc[0] = r.c0[0]; sn[0] = r.c0[1]; cc[1] = r.c0[2]; sn[1] = r.c0[3]; cc[2] = r.c1[0]; sn[2] = r.c1[1]; cc[3] = r.c1[2]; sn[3] = r.c1[3];
;     float ol[4], oh[4];
; #pragma unroll
;     for (int i = 0; i < NH; ++i) {
;         const float c = rope ? cc[i] : 1.0f, sv = rope ? sn[i] : 0.0f;
;         ol[i] = (lo[i] * c - hi[i] * sv) * scale; oh[i] = (hi[i] * c + lo[i] * sv) * scale;
;     }
;     if (NH == 4) {
;         u32x2 w0, w1; w0.x = pg8::cvt_pk_bf16(ol[0], ol[1]); w0.y = pg8::cvt_pk_bf16(ol[2], ol[3]); w1.x = pg8::cvt_pk_bf16(oh[0], oh[1]); w1.y = pg8::cvt_pk_bf16(oh[2], oh[3]);
;         *(u32x2*)(dst + sub * 4) = w0; *(u32x2*)(dst + 32 + sub * 4) = w1;
;     } else {
;         *(unsigned*)(dst + sub * 2) = pg8::cvt_pk_bf16(ol[0], ol[1]); *(unsigned*)(dst + 16 + sub * 2) = pg8::cvt_pk_bf16(oh[0], oh[1]);
;     }
; }
	v_add_f32_e32 v18, v18, v19
	v_fmamk_f32 v18, v18, 0x3c800000, v231
	v_rsq_f32_e32 v18, v18
	s_nop 0
	v_pk_mul_f32 v[28:29], v[50:51], v[18:19] op_sel_hi:[1,0]
	s_nop 0
	v_pk_mul_f32 v[24:25], v[28:29], v[24:25]
	v_pk_mul_f32 v[28:29], v[2:3], v[18:19] op_sel_hi:[1,0]
	s_nop 0
	v_pk_mul_f32 v[26:27], v[28:29], v[26:27]
	v_pk_mul_f32 v[28:29], v[42:43], v[18:19] op_sel_hi:[1,0]
	v_pk_mul_f32 v[18:19], v[4:5], v[18:19] op_sel_hi:[1,0]
	v_pk_mul_f32 v[14:15], v[28:29], v[14:15]
	v_pk_mul_f32 v[16:17], v[18:19], v[16:17]
	v_fmamk_f32 v18, v24, 0x80000000, v25
	v_fmac_f32_e32 v24, 0, v25
	v_mul_f32_e32 v19, v54, v24
	v_fmamk_f32 v24, v26, 0x80000000, v27
	v_fmac_f32_e32 v26, 0, v27
	v_mul_f32_e32 v25, v54, v26
	v_fmamk_f32 v26, v14, 0x80000000, v15
	v_fmac_f32_e32 v14, 0, v15
	v_mul_f32_e32 v27, v54, v14
	v_fmamk_f32 v14, v16, 0x80000000, v17
	v_mul_f32_e32 v18, v54, v18
	v_mul_f32_e32 v15, v54, v14
	v_fmac_f32_e32 v16, 0, v17
	v_mul_f32_e32 v24, v54, v24
	v_mul_f32_e32 v26, v54, v26
	v_mul_f32_e32 v17, v54, v16
	v_cvt_pk_bf16_f32 v14, v18, v24
	v_cvt_pk_bf16_f32 v15, v26, v15
	v_cvt_pk_bf16_f32 v16, v19, v25
	v_lshl_add_u64 v[18:19], v[34:35], 0, v[10:11]
	v_cvt_pk_bf16_f32 v17, v27, v17
	global_store_dwordx2 v[18:19], v[14:15], off
	global_store_dwordx2 v[18:19], v[16:17], off offset:64
	s_waitcnt vmcnt(6)
	v_lshlrev_b32_e32 v14, 16, v21
	v_and_b32_e32 v16, 0xffff0000, v21
	v_lshlrev_b32_e32 v15, 16, v23
	v_and_b32_e32 v17, 0xffff0000, v23
	v_mov_b32_e32 v24, v16
	v_mov_b32_e32 v25, v14
	v_mov_b32_e32 v18, v17
	v_mov_b32_e32 v19, v15
	v_pk_mul_f32 v[24:25], v[24:25], v[24:25]
	v_and_b32_e32 v21, 0xffff0000, v22
	v_pk_fma_f32 v[18:19], v[18:19], v[18:19], v[24:25]
	v_lshlrev_b32_e32 v24, 16, v20
	v_and_b32_e32 v20, 0xffff0000, v20
	v_lshlrev_b32_e32 v25, 16, v22
	v_mov_b32_e32 v26, v24
	v_mov_b32_e32 v27, v20
	v_mov_b32_e32 v22, v25
	v_mov_b32_e32 v23, v21
	v_pk_mul_f32 v[26:27], v[26:27], v[26:27]
	v_lshl_add_u64 v[10:11], v[12:13], 0, v[10:11]
	v_pk_fma_f32 v[22:23], v[22:23], v[22:23], v[26:27]
	s_nop 0
	v_add_f32_e32 v22, v22, v23
	v_add_f32_e32 v19, v19, v22
	v_add_f32_e32 v18, v18, v19
	s_nop 1
	v_mov_b32_dpp v19, v18 quad_perm:[1,0,3,2] row_mask:0xf bank_mask:0xf
	s_waitcnt lgkmcnt(0)
	v_add_f32_e32 v18, v18, v19
	s_nop 1
	v_mov_b32_dpp v19, v18 quad_perm:[2,3,0,1] row_mask:0xf bank_mask:0xf
	s_waitcnt lgkmcnt(0)
	v_add_f32_e32 v18, v18, v19
	s_nop 1
	v_mov_b32_dpp v19, v18 row_shl:4 row_mask:0xf bank_mask:0x5
	v_mov_b32_dpp v19, v18 row_shr:4 row_mask:0xf bank_mask:0xa
	s_waitcnt lgkmcnt(0)
	v_add_f32_e32 v18, v18, v19
	v_fmamk_f32 v18, v18, 0x3c800000, v231
	v_rsq_f32_e32 v18, v18
	s_nop 0
	v_pk_mul_f32 v[2:3], v[2:3], v[18:19] op_sel_hi:[1,0]
	s_nop 0
	v_pk_mul_f32 v[2:3], v[2:3], v[20:21]
	v_pk_mul_f32 v[20:21], v[42:43], v[18:19] op_sel_hi:[1,0]
	v_pk_mul_f32 v[22:23], v[50:51], v[18:19] op_sel_hi:[1,0]
	v_pk_mul_f32 v[14:15], v[20:21], v[14:15]
	v_pk_mul_f32 v[4:5], v[4:5], v[18:19] op_sel_hi:[1,0]
	v_fmamk_f32 v18, v2, 0x80000000, v3
	v_fmac_f32_e32 v2, 0, v3
	v_pk_mul_f32 v[22:23], v[22:23], v[24:25]
	v_pk_mul_f32 v[4:5], v[4:5], v[16:17]
	v_mul_f32_e32 v19, v54, v2
	v_fmamk_f32 v2, v14, 0x80000000, v15
	v_fmamk_f32 v16, v22, 0x80000000, v23
	v_mul_f32_e32 v3, v54, v2
	v_fmamk_f32 v2, v4, 0x80000000, v5
	v_fmac_f32_e32 v4, 0, v5
	v_mul_f32_e32 v16, v54, v16
	v_fmac_f32_e32 v22, 0, v23
	v_mul_f32_e32 v18, v54, v18
	v_fmac_f32_e32 v14, 0, v15
	v_mul_f32_e32 v15, v54, v2
	v_mul_f32_e32 v5, v54, v4
	v_cvt_pk_bf16_f32 v2, v16, v18
	v_cvt_pk_bf16_f32 v3, v3, v15
	v_mul_f32_e32 v17, v54, v22
	v_mul_f32_e32 v14, v54, v14
	v_cvt_pk_bf16_f32 v4, v17, v19
	v_cvt_pk_bf16_f32 v5, v14, v5
	global_store_dwordx2 v[10:11], v[2:3], off
	global_store_dwordx2 v[10:11], v[4:5], off offset:64
	s_andn2_b64 exec, exec, s[10:11]
	s_cbranch_execnz .LBB0_4225

; template <int D> __device__ __forceinline__ void hv_load(HVRaw& r, const bf16_t* __restrict__ src, const float* __restrict__ gain, const f32x2* __restrict__ cs, const int sub) {
;     if (D == 64) {
;         r.a = *(const u32x2*)(src + sub * 4); r.b = *(const u32x2*)(src + 32 + sub * 4);
;         r.g0 = *(const f32x4*)(gain + sub * 4); r.g1 = *(const f32x4*)(gain + 32 + sub * 4);
;         r.c0 = *(const f32x4*)(cs + sub * 4); r.c1 = *(const f32x4*)(cs + sub * 4 + 2);
;     } else {
;         r.a.x = *(const unsigned*)(src + sub * 2); r.b.x = *(const unsigned*)(src + 16 + sub * 2); r.a.y = 0u; r.b.y = 0u;
;         const f32x2 g0 = *(const f32x2*)(gain + sub * 2), g1 = *(const f32x2*)(gain + 16 + sub * 2);
;         r.g0 = (f32x4){g0.x, g0.y, 0.f, 0.f}; r.g1 = (f32x4){g1.x, g1.y, 0.f, 0.f};
;         r.c0 = *(const f32x4*)(cs + sub * 2); r.c1 = r.c0;
;     }
; }
; template <int D> __device__ __forceinline__ void hv_finish(const HVRaw& r, bool norm, bool rope, float scale, bf16_t* __restrict__ dst, const int sub) {
;     constexpr int NH = D / 16;
;     float lo[4], hi[4], cc[4], sn[4];
;     lo[0] = bf2f(r.a.x & 0xffffu); lo[1] = bf2f(r.a.x >> 16); lo[2] = bf2f(r.a.y & 0xffffu); lo[3] = bf2f(r.a.y >> 16);
;     hi[0] = bf2f(r.b.x & 0xffffu); hi[1] = bf2f(r.b.x >> 16); hi[2] = bf2f(r.b.y & 0xffffu); hi[3] = bf2f(r.b.y >> 16);
;     float ss = 0.f;
; #pragma unroll
; __global__ void __launch_bounds__(512, 2) mega_fwd(KArgs a) {
;     ...
;             for (int e0 = gw * 64 + lane; e0 < T_ * 8 * 8; e0 += NGW * 64 * 2) {
;                 HVRaw hr[2]; u32x2 kr[2];
;                 const int sub = lane & 7;
; #pragma unroll
;                 for (int u2 = 0; u2 < 2; ++u2) {
;                     const int ev = (e0 + u2 * NGW * 64) >> 3, t = ev >> 3, h = ev & 7;
;                     hv_load<32>(hr[u2], RA + (size_t)t * 1792 + h * 96 + 64, mqg + 64, CS32 + (size_t)t * 16, sub);
;                     kr[u2] = *(const u32x2*)(KROPE + (size_t)t * 32 + sub * 4);
;                 }
; #pragma unroll
;                 for (int u2 = 0; u2 < 2; ++u2) {
;                     const int ev = (e0 + u2 * NGW * 64) >> 3, t = ev >> 3, h = ev & 7;
;                     hv_finish<32>(hr[u2], true, true, SCQ, QM + ((size_t)t * 8 + h) * 96 + 64, sub);
;                     *(u32x2*)(KM + ((size_t)t * 8 + h) * 96 + 64 + sub * 4) = kr[u2];
;                 }
;             }
.LBB0_4228:
	v_bfe_u32 v7, v1, 3, 3
	v_mul_u32_u24_e32 v2, 0x60, v7
	v_lshlrev_b32_e32 v2, 1, v2
	v_mov_b32_e32 v3, v0
	v_lshl_add_u64 v[2:3], s[6:7], 0, v[2:3]
	v_ashrrev_i32_e32 v32, 6, v1
	v_mad_i64_i32 v[4:5], s[8:9], v32, s74, v[2:3]
	v_mov_b32_e32 v15, v0
	v_lshl_add_u64 v[4:5], v[4:5], 0, v[14:15]
	v_add_co_u32_e32 v4, vcc, s76, v4
	global_load_dwordx2 v[20:21], v[8:9], off offset:256
	global_load_dwordx2 v[18:19], v[8:9], off offset:320
	v_addc_co_u32_e32 v5, vcc, 0, v5, vcc
	global_load_dword v17, v[4:5], off offset:128
	global_load_dword v36, v[4:5], off offset:160
	v_ashrrev_i32_e32 v33, 31, v32
	v_lshlrev_b64 v[22:23], 7, v[32:33]
	v_lshl_add_u64 v[4:5], v[10:11], 0, v[22:23]
	global_load_dwordx4 v[28:31], v[4:5], off
	v_lshlrev_b64 v[4:5], 6, v[32:33]
	v_lshl_add_u64 v[4:5], v[12:13], 0, v[4:5]
	global_load_dwordx2 v[22:23], v[4:5], off
	v_add_u32_e32 v4, 0x20000, v1
	v_ashrrev_i32_e32 v26, 6, v4
	v_mad_i64_i32 v[2:3], s[8:9], v26, s74, v[2:3]
	v_lshl_add_u64 v[2:3], v[2:3], 0, v[14:15]
	v_add_co_u32_e32 v2, vcc, s76, v2
	v_ashrrev_i32_e32 v27, 31, v26
	s_nop 0
	v_addc_co_u32_e32 v3, vcc, 0, v3, vcc
	global_load_dword v37, v[2:3], off offset:128
	global_load_dword v38, v[2:3], off offset:160
	v_lshlrev_b64 v[4:5], 7, v[26:27]
	v_lshl_add_u64 v[2:3], v[10:11], 0, v[4:5]
	global_load_dwordx4 v[2:5], v[2:3], off
	v_lshlrev_b64 v[24:25], 6, v[26:27]
	v_lshl_or_b32 v27, v32, 3, v7
	v_mov_b64_e32 v[32:33], s[6:7]
	v_mad_i64_i32 v[34:35], s[8:9], v27, s27, v[32:33]
	v_lshl_add_u64 v[24:25], v[12:13], 0, v[24:25]
	global_load_dwordx2 v[24:25], v[24:25], off
	s_mov_b32 s8, 0x14400000
	v_lshl_or_b32 v7, v26, 3, v7
	s_waitcnt vmcnt(7)
	v_lshlrev_b32_e32 v27, 16, v17
	s_waitcnt vmcnt(6)
	v_lshlrev_b32_e32 v39, 16, v36
	v_and_b32_e32 v36, 0xffff0000, v36
	v_and_b32_e32 v17, 0xffff0000, v17
	v_mul_f32_e32 v40, v39, v39
	v_mul_f32_e32 v41, v36, v36
	v_fmac_f32_e32 v40, v27, v27
	v_fmac_f32_e32 v41, v17, v17
	v_add_f32_e32 v40, v40, v41
	s_nop 1
	v_mov_b32_dpp v41, v40 quad_perm:[1,0,3,2] row_mask:0xf bank_mask:0xf
	s_waitcnt lgkmcnt(0)
	v_add_f32_e32 v40, v40, v41
	s_nop 1
	v_mov_b32_dpp v41, v40 quad_perm:[2,3,0,1] row_mask:0xf bank_mask:0xf
	s_waitcnt vmcnt(3)
	v_and_b32_e32 v26, 0xffff0000, v37
	s_waitcnt lgkmcnt(0)
	v_add_f32_e32 v40, v40, v41
	s_nop 1
	v_mov_b32_dpp v41, v40 row_shl:4 row_mask:0xf bank_mask:0x5
	v_mov_b32_dpp v41, v40 row_shr:4 row_mask:0xf bank_mask:0xa
	s_waitcnt lgkmcnt(0)
	v_add_f32_e32 v40, v40, v41
	v_fmamk_f32 v40, v40, 0x3d000000, v231
	v_rsq_f32_e32 v40, v40
	s_nop 0
	v_mul_f32_e32 v41, v20, v40
	v_mul_f32_e32 v27, v41, v27
	v_mul_f32_e32 v41, v18, v40
	v_mul_f32_e32 v39, v41, v39
	v_mul_f32_e32 v41, v21, v40
	v_mul_f32_e32 v40, v19, v40
	v_mul_f32_e32 v36, v40, v36
	v_mul_f32_e32 v40, v29, v39
	v_fma_f32 v40, v28, v27, -v40
	v_mul_f32_e32 v27, v29, v27
	v_mul_f32_e32 v17, v41, v17
	v_fmac_f32_e32 v27, v28, v39
	v_mul_f32_e32 v28, v31, v36
	v_fma_f32 v28, v30, v17, -v28
	v_mul_f32_e32 v28, 0x3e16c740, v28
	v_mul_f32_e32 v17, v31, v17
	v_mul_f32_e32 v40, 0x3e16c740, v40
	v_fmac_f32_e32 v17, v30, v36
	v_cvt_pk_bf16_f32 v30, v40, v28
	v_lshl_add_u64 v[28:29], v[34:35], 0, v[14:15]
	v_add_co_u32_e32 v28, vcc, s20, v28
	v_mul_f32_e32 v17, 0x3e16c740, v17
	s_nop 0
	v_addc_co_u32_e32 v29, vcc, 0, v29, vcc
	v_mul_f32_e32 v27, 0x3e16c740, v27
	global_store_dword v[28:29], v30, off offset:128
	v_cvt_pk_bf16_f32 v17, v27, v17
	global_store_dword v[28:29], v17, off offset:160
	v_mov_b32_e32 v17, v0
	v_lshl_add_u64 v[28:29], v[34:35], 0, v[16:17]
	v_add_co_u32_e32 v28, vcc, s8, v28
	s_waitcnt vmcnt(4)
	v_lshlrev_b32_e32 v27, 16, v38
	v_addc_co_u32_e32 v29, vcc, 0, v29, vcc
	global_store_dwordx2 v[28:29], v[22:23], off offset:128
	v_and_b32_e32 v28, 0xffff0000, v38
	v_mad_i64_i32 v[22:23], s[8:9], v7, s27, v[32:33]
	v_lshlrev_b32_e32 v7, 16, v37
	v_mul_f32_e32 v29, v27, v27
	v_mul_f32_e32 v30, v28, v28
	v_fmac_f32_e32 v29, v7, v7
	v_fmac_f32_e32 v30, v26, v26
	v_add_f32_e32 v29, v29, v30
	s_nop 1
	v_mov_b32_dpp v30, v29 quad_perm:[1,0,3,2] row_mask:0xf bank_mask:0xf
	s_mov_b32 s8, 0xbffff
	s_waitcnt lgkmcnt(0)
	v_add_f32_e32 v29, v29, v30
	s_nop 1
	v_mov_b32_dpp v30, v29 quad_perm:[2,3,0,1] row_mask:0xf bank_mask:0xf
	s_waitcnt lgkmcnt(0)
	v_add_f32_e32 v29, v29, v30
	s_nop 1
	v_mov_b32_dpp v30, v29 row_shl:4 row_mask:0xf bank_mask:0x5
	v_mov_b32_dpp v30, v29 row_shr:4 row_mask:0xf bank_mask:0xa
	s_waitcnt lgkmcnt(0)
	v_add_f32_e32 v29, v29, v30
	v_fmamk_f32 v29, v29, 0x3d000000, v231
	v_rsq_f32_e32 v29, v29
	s_nop 0
	v_mul_f32_e32 v20, v20, v29
	v_mul_f32_e32 v18, v18, v29
	v_mul_f32_e32 v7, v20, v7
	v_mul_f32_e32 v18, v18, v27
	v_mul_f32_e32 v19, v19, v29
	v_mul_f32_e32 v20, v21, v29
	v_mul_f32_e32 v19, v19, v28
	s_waitcnt vmcnt(4)
	v_mul_f32_e32 v21, v3, v18
	v_mul_f32_e32 v3, v3, v7
	v_mul_f32_e32 v20, v20, v26
	v_fma_f32 v21, v2, v7, -v21
	v_fmac_f32_e32 v3, v2, v18
	v_mul_f32_e32 v2, v5, v19
	v_mul_f32_e32 v7, 0x3e16c740, v3
	v_fma_f32 v2, v4, v20, -v2
	v_mul_f32_e32 v3, v5, v20
	v_mul_f32_e32 v2, 0x3e16c740, v2
	v_fmac_f32_e32 v3, v4, v19
	v_mul_f32_e32 v21, 0x3e16c740, v21
	v_mul_f32_e32 v4, 0x3e16c740, v3
	v_cvt_pk_bf16_f32 v5, v21, v2
	v_lshl_add_u64 v[2:3], v[22:23], 0, v[14:15]
	v_add_co_u32_e32 v2, vcc, s20, v2
	s_nop 1
	v_addc_co_u32_e32 v3, vcc, 0, v3, vcc
	global_store_dword v[2:3], v5, off offset:128
	v_cvt_pk_bf16_f32 v4, v7, v4
	global_store_dword v[2:3], v4, off offset:160
	v_lshl_add_u64 v[2:3], v[22:23], 0, v[16:17]
	v_add_co_u32_e32 v2, vcc, 0x14400000, v2
	s_nop 1
	v_addc_co_u32_e32 v3, vcc, 0, v3, vcc
	v_cmp_lt_i32_e32 vcc, s8, v1
	v_add_u32_e32 v1, 0x40000, v1
	s_or_b64 s[2:3], vcc, s[2:3]
	s_waitcnt vmcnt(5)
	global_store_dwordx2 v[2:3], v[24:25], off offset:128
	s_andn2_b64 exec, exec, s[2:3]
	s_cbranch_execnz .LBB0_4228
